# adds: P8 cross-attention waves 4-7 staggered by one stage (s_sleep 32 after the K-staging barrier) so softmax VALU overlaps partner MFMAs
# speedup vs baseline: 1.0048x; 1.0048x over previous
; #define LAS __attribute__((address_space(3)))
; #define MFMA16(a, b, c) __builtin_amdgcn_mfma_f32_16x16x32_bf16((a), (b), (c), 0, 0, 0)
; __device__ __forceinline__ void xattn_pair(LAS unsigned char* lds, int bh, size_t row_base, bf16* QO, const bf16* Kx, const bf16* VTx, int tid, const WsRef& wsr) {
;     ...
;     const u32x4* kg = (const u32x4*)(Kx + (size_t)bh * 65536);
; #pragma unroll 4
;     for (int i = 0; i < 16; ++i) { const int id = tid + 512 * i, r = id >> 5, ch = id & 31; *(LAS u32x4*)(T + r * LDX + ch * 8) = kg[id]; }
;     __syncthreads();
;     bf16x8 pf0[8], pf1[8]; float rinv0, rinv1;
; #pragma unroll
;     for (int half = 0; half < 2; ++half) {
;         const bf16* qp = half ? qp1 : qp0;
;         bf16x8 qf[8];
; #pragma unroll
;         for (int kk = 0; kk < 8; ++kk) qf[kk] = *(const bf16x8*)(qp + kk * 32 + fq * 8);
;         f32x4 sx[16];
; #pragma unroll
;         for (int n = 0; n < 16; ++n) sx[n] = (f32x4){0.f, 0.f, 0.f, 0.f};
; #pragma unroll
;         for (int kk = 0; kk < 8; ++kk)
; #pragma unroll
;             for (int n = 0; n < 16; ++n) { const bf16x8 kf = *(const LAS bf16x8*)(T + (n * 16 + fr) * LDX + kk * 32 + fq * 8); sx[n] = MFMA16(kf, qf[kk], sx[n]); }
.LBB0_704:
	v_lshl_add_u64 v[16:17], v[84:85], 0, s[8:9]
	v_add_co_u32_e32 v12, vcc, 0x2200000, v16
	s_add_u32 s8, s8, 0x8000
	s_nop 0
	v_addc_co_u32_e32 v13, vcc, 0, v17, vcc
	v_add_co_u32_e32 v14, vcc, 0x2202000, v16
	s_addc_u32 s9, s9, 0
	s_nop 0
	v_addc_co_u32_e32 v15, vcc, 0, v17, vcc
	v_add_co_u32_e32 v18, vcc, 0x2204000, v16
	global_load_dwordx4 v[4:7], v[12:13], off
	global_load_dwordx4 v[8:11], v[14:15], off
	v_addc_co_u32_e32 v19, vcc, 0, v17, vcc
	v_add_co_u32_e32 v16, vcc, 0x2206000, v16
	global_load_dwordx4 v[12:15], v[18:19], off
	s_nop 0
	v_addc_co_u32_e32 v17, vcc, 0, v17, vcc
	global_load_dwordx4 v[16:19], v[16:17], off
	s_cmp_eq_u32 s8, 0x20000
	s_waitcnt vmcnt(0)
	ds_write_b128 v1, v[4:7]
	v_add_u32_e32 v1, 0x8400, v1
	ds_write_b128 v2, v[8:11]
	v_add_u32_e32 v2, 0x8400, v2
	ds_write_b128 v0, v[12:15]
	v_add_u32_e32 v0, 0x8400, v0
	ds_write_b128 v3, v[16:19]
	v_add_u32_e32 v3, 0x8400, v3
	s_cbranch_scc0 .LBB0_704
	s_ashr_i32 s13, s12, 31
	v_lshrrev_b32_e32 v0, 2, v128
	s_lshl_b64 s[8:9], s[12:13], 8
	v_and_b32_e32 v100, 15, v128
	v_and_b32_e32 v0, 0xf0, v0
	v_or3_b32 v0, s8, v100, v0
	v_mov_b32_e32 v1, s9
	v_lshlrev_b64 v[0:1], 11, v[0:1]
	s_lshl_b32 s8, s33, 9
	v_lshl_add_u64 v[0:1], s[70:71], 0, v[0:1]
	s_and_b32 s8, s8, 0x600
	s_mov_b32 s9, 0
	v_lshl_add_u64 v[96:97], v[0:1], 0, s[8:9]
	v_bfe_u32 v0, v128, 4, 2
	v_lshlrev_b32_e32 v86, 4, v0
	v_mov_b32_e32 v87, 0
	v_lshl_add_u64 v[28:29], v[96:97], 0, v[86:87]
	s_waitcnt lgkmcnt(0)
	s_barrier
	v_lshlrev_b32_e32 v109, 3, v0
	global_load_dwordx4 v[36:39], v[28:29], off
	global_load_dwordx4 v[24:27], v[28:29], off offset:64
	global_load_dwordx4 v[20:23], v[28:29], off offset:128
	global_load_dwordx4 v[16:19], v[28:29], off offset:192
	global_load_dwordx4 v[12:15], v[28:29], off offset:256
	global_load_dwordx4 v[8:11], v[28:29], off offset:320
	global_load_dwordx4 v[4:7], v[28:29], off offset:384
	global_load_dwordx4 v[0:3], v[28:29], off offset:448
	v_readfirstlane_b32 s8, v128
	s_nop 0
	s_cmpk_lt_u32 s8, 0x100
	s_cbranch_scc1 .Lp8_lead
	s_sleep 32
.Lp8_lead:
	s_mov_b64 s[8:9], 0x40000
	v_lshl_add_u64 v[98:99], v[96:97], 0, s[8:9]
	v_add_u32_e32 v95, 0, v86
	s_movk_i32 s8, 0x210
	v_mad_u32_u24 v94, v100, s8, v95
	ds_read_b128 v[28:31], v94
	v_mov_b32_e32 v101, 0x1ef00
	v_mad_u32_u24 v101, v100, s8, v101
	v_add_u32_e32 v163, v95, v101
	ds_read_b128 v[118:121], v163
	v_mov_b32_e32 v32, 0x12900
	v_mov_b32_e32 v40, 0x14a00
	v_mad_u32_u24 v103, v100, s8, v32
	v_mad_u32_u24 v106, v100, s8, v40
	v_add_u32_e32 v157, v95, v103
	v_add_u32_e32 v158, v95, v106
	v_mul_u32_u24_e32 v88, 0x210, v100
	v_or_b32_e32 v93, 0x400, v128
	s_waitcnt vmcnt(7) lgkmcnt(1)
	v_mfma_f32_16x16x32_bf16 v[110:113], v[28:31], v[36:39], 0
	ds_read_b128 v[28:31], v94 offset:8448
	ds_read_b128 v[32:35], v157
	ds_read_b128 v[40:43], v158
	s_waitcnt lgkmcnt(2)
	v_mfma_f32_16x16x32_bf16 v[114:117], v[28:31], v[36:39], 0
	ds_read_b128 v[28:31], v94 offset:16896
	s_waitcnt lgkmcnt(0)
	v_mfma_f32_16x16x32_bf16 v[80:83], v[28:31], v[36:39], 0
	ds_read_b128 v[28:31], v94 offset:25344
	s_waitcnt lgkmcnt(0)
	v_mfma_f32_16x16x32_bf16 v[76:79], v[28:31], v[36:39], 0
	ds_read_b128 v[28:31], v94 offset:33792
	s_waitcnt lgkmcnt(0)
	v_mfma_f32_16x16x32_bf16 v[72:75], v[28:31], v[36:39], 0
	ds_read_b128 v[28:31], v94 offset:42240
	v_mfma_f32_16x16x32_bf16 v[44:47], v[40:43], v[36:39], 0
	v_mov_b32_e32 v40, 0x16b00
	v_mad_u32_u24 v108, v100, s8, v40
	v_add_u32_e32 v159, v95, v108
	s_waitcnt lgkmcnt(0)
	v_mfma_f32_16x16x32_bf16 v[68:71], v[28:31], v[36:39], 0
	ds_read_b128 v[28:31], v94 offset:50688
	ds_read_b128 v[40:43], v159
	s_waitcnt lgkmcnt(0)
	v_mfma_f32_16x16x32_bf16 v[56:59], v[40:43], v[36:39], 0
	v_mov_b32_e32 v40, 0x18c00
	v_mad_u32_u24 v107, v100, s8, v40
	v_add_u32_e32 v160, v95, v107
	v_mfma_f32_16x16x32_bf16 v[64:67], v[28:31], v[36:39], 0
	ds_read_b128 v[28:31], v94 offset:59136
	ds_read_b128 v[40:43], v160
	s_waitcnt lgkmcnt(1)
	v_mfma_f32_16x16x32_bf16 v[60:63], v[28:31], v[36:39], 0
	v_mov_b32_e32 v28, 0x10800
	v_mad_u32_u24 v97, v100, s8, v28
	v_add_u32_e32 v156, v95, v97
	s_waitcnt lgkmcnt(0)
	v_mfma_f32_16x16x32_bf16 v[52:55], v[40:43], v[36:39], 0
	v_mov_b32_e32 v40, 0x1ad00
	v_mad_u32_u24 v105, v100, s8, v40
	v_add_u32_e32 v161, v95, v105
	ds_read_b128 v[28:31], v156
	ds_read_b128 v[40:43], v161
	s_waitcnt lgkmcnt(0)
	v_mfma_f32_16x16x32_bf16 v[48:51], v[40:43], v[36:39], 0
	v_mov_b32_e32 v40, 0x1ce00
	v_mad_u32_u24 v104, v100, s8, v40
	v_add_u32_e32 v162, v95, v104
	ds_read_b128 v[40:43], v162
	v_mfma_f32_16x16x32_bf16 v[28:31], v[28:31], v[36:39], 0
	v_add_u32_e32 v100, 64, v95
	v_add_u32_e32 v164, v100, v97
	v_add_u32_e32 v165, v100, v103
	v_mfma_f32_16x16x32_bf16 v[32:35], v[32:35], v[36:39], 0
	v_add_u32_e32 v166, v100, v106
	v_add_u32_e32 v167, v100, v108
	v_add_u32_e32 v168, v100, v107
	s_waitcnt lgkmcnt(0)
	v_mfma_f32_16x16x32_bf16 v[40:43], v[40:43], v[36:39], 0
	v_add_u32_e32 v169, v100, v105
	v_add_u32_e32 v170, v100, v104
	v_add_u32_e32 v171, v100, v101
	v_mfma_f32_16x16x32_bf16 v[36:39], v[118:121], v[36:39], 0
	ds_read_b128 v[118:121], v94 offset:64
	v_add_u32_e32 v100, 0x80, v95
	v_add_u32_e32 v172, v100, v97
	s_waitcnt vmcnt(6) lgkmcnt(0)
	v_mfma_f32_16x16x32_bf16 v[110:113], v[118:121], v[24:27], v[110:113]
	ds_read_b128 v[118:121], v94 offset:8512
	v_add_u32_e32 v173, v100, v103
	v_add_u32_e32 v174, v100, v106
	s_waitcnt lgkmcnt(0)
	v_mfma_f32_16x16x32_bf16 v[114:117], v[118:121], v[24:27], v[114:117]
	ds_read_b128 v[118:121], v94 offset:16960
	v_add_u32_e32 v175, v100, v108
	v_add_u32_e32 v176, v100, v107
	s_waitcnt lgkmcnt(0)
; #define LAS __attribute__((address_space(3)))
; #define MFMA16(a, b, c) __builtin_amdgcn_mfma_f32_16x16x32_bf16((a), (b), (c), 0, 0, 0)
; __device__ __forceinline__ void xattn_pair(LAS unsigned char* lds, int bh, size_t row_base, bf16* QO, const bf16* Kx, const bf16* VTx, int tid, const WsRef& wsr) {
;     ...
; #pragma unroll
;         for (int kk = 0; kk < 8; ++kk)
; #pragma unroll
;             for (int n = 0; n < 16; ++n) { const bf16x8 kf = *(const LAS bf16x8*)(T + (n * 16 + fr) * LDX + kk * 32 + fq * 8); sx[n] = MFMA16(kf, qf[kk], sx[n]); }
	v_mfma_f32_16x16x32_bf16 v[80:83], v[118:121], v[24:27], v[80:83]
	ds_read_b128 v[118:121], v94 offset:25408
	v_add_u32_e32 v177, v100, v105
	v_add_u32_e32 v178, v100, v104
	s_waitcnt lgkmcnt(0)
	v_mfma_f32_16x16x32_bf16 v[76:79], v[118:121], v[24:27], v[76:79]
	ds_read_b128 v[118:121], v94 offset:33856
	v_add_u32_e32 v179, v100, v101
	v_add_u32_e32 v100, 0xc0, v95
	s_waitcnt lgkmcnt(0)
	v_mfma_f32_16x16x32_bf16 v[72:75], v[118:121], v[24:27], v[72:75]
	ds_read_b128 v[118:121], v94 offset:42304
	v_add_u32_e32 v180, v100, v97
	v_add_u32_e32 v181, v100, v103
	s_waitcnt lgkmcnt(0)
	v_mfma_f32_16x16x32_bf16 v[68:71], v[118:121], v[24:27], v[68:71]
	ds_read_b128 v[118:121], v94 offset:50752
	v_add_u32_e32 v182, v100, v106
	v_add_u32_e32 v183, v100, v108
	s_waitcnt lgkmcnt(0)
	v_mfma_f32_16x16x32_bf16 v[64:67], v[118:121], v[24:27], v[64:67]
	ds_read_b128 v[118:121], v94 offset:59200
	v_add_u32_e32 v184, v100, v107
	v_add_u32_e32 v185, v100, v105
	s_waitcnt lgkmcnt(0)
	v_mfma_f32_16x16x32_bf16 v[60:63], v[118:121], v[24:27], v[60:63]
	ds_read_b128 v[118:121], v164
	v_add_u32_e32 v186, v100, v104
	v_add_u32_e32 v187, v100, v101
	s_waitcnt lgkmcnt(0)
	v_mfma_f32_16x16x32_bf16 v[28:31], v[118:121], v[24:27], v[28:31]
	ds_read_b128 v[118:121], v165
	v_add_u32_e32 v100, 0x100, v95
	v_add_u32_e32 v188, v100, v97
	s_waitcnt lgkmcnt(0)
	v_mfma_f32_16x16x32_bf16 v[32:35], v[118:121], v[24:27], v[32:35]
	ds_read_b128 v[118:121], v166
	v_add_u32_e32 v189, v100, v103
	v_add_u32_e32 v190, v100, v106
	s_waitcnt lgkmcnt(0)
	v_mfma_f32_16x16x32_bf16 v[118:121], v[118:121], v[24:27], v[44:47]
	s_nop 2
	ds_read_b128 v[44:47], v167
	v_add_u32_e32 v191, v100, v108
	v_add_u32_e32 v192, v100, v107
	s_waitcnt lgkmcnt(0)
	v_mfma_f32_16x16x32_bf16 v[56:59], v[44:47], v[24:27], v[56:59]
	ds_read_b128 v[44:47], v168
	v_add_u32_e32 v195, v100, v101
	v_add_u32_e32 v193, v100, v105
	s_waitcnt lgkmcnt(0)
	v_mfma_f32_16x16x32_bf16 v[52:55], v[44:47], v[24:27], v[52:55]
	ds_read_b128 v[44:47], v169
	v_add_u32_e32 v194, v100, v104
	v_add_u32_e32 v100, 0x140, v95
	s_waitcnt lgkmcnt(0)
	v_mfma_f32_16x16x32_bf16 v[122:125], v[44:47], v[24:27], v[48:51]
	ds_read_b128 v[44:47], v170
	v_add_u32_e32 v199, v100, v97
	v_add_u32_e32 v196, v100, v103
	s_waitcnt lgkmcnt(0)
	v_mfma_f32_16x16x32_bf16 v[130:133], v[44:47], v[24:27], v[40:43]
	s_nop 2
	ds_read_b128 v[40:43], v171
	v_add_u32_e32 v197, v100, v106
	v_add_u32_e32 v198, v100, v108
	s_waitcnt lgkmcnt(0)
	v_mfma_f32_16x16x32_bf16 v[134:137], v[40:43], v[24:27], v[36:39]
	ds_read_b128 v[24:27], v94 offset:128
	v_add_u32_e32 v200, v100, v107
	v_add_u32_e32 v201, v100, v105
	s_waitcnt vmcnt(5) lgkmcnt(0)
	v_mfma_f32_16x16x32_bf16 v[110:113], v[24:27], v[20:23], v[110:113]
	ds_read_b128 v[24:27], v94 offset:8576
	v_add_u32_e32 v202, v100, v104
	v_add_u32_e32 v203, v100, v101
	s_waitcnt lgkmcnt(0)
	v_mfma_f32_16x16x32_bf16 v[114:117], v[24:27], v[20:23], v[114:117]
	ds_read_b128 v[24:27], v94 offset:17024
	v_add_u32_e32 v100, 0x180, v95
	v_add_u32_e32 v209, v100, v97
	s_waitcnt lgkmcnt(0)
	v_mfma_f32_16x16x32_bf16 v[80:83], v[24:27], v[20:23], v[80:83]
	ds_read_b128 v[24:27], v94 offset:25472
	v_add_u32_e32 v211, v100, v103
	v_add_u32_e32 v215, v100, v106
	s_waitcnt lgkmcnt(0)
	v_mfma_f32_16x16x32_bf16 v[76:79], v[24:27], v[20:23], v[76:79]
	ds_read_b128 v[24:27], v94 offset:33920
	v_add_u32_e32 v216, v100, v108
	v_add_u32_e32 v217, v100, v107
	s_waitcnt lgkmcnt(0)
	v_mfma_f32_16x16x32_bf16 v[72:75], v[24:27], v[20:23], v[72:75]
	ds_read_b128 v[24:27], v94 offset:42368
	v_add_u32_e32 v218, v100, v105
	v_add_u32_e32 v219, v100, v104
	s_waitcnt lgkmcnt(0)
	v_mfma_f32_16x16x32_bf16 v[68:71], v[24:27], v[20:23], v[68:71]
	ds_read_b128 v[24:27], v94 offset:50816
	v_add_u32_e32 v220, v100, v101
	v_add_u32_e32 v95, 0x1c0, v95
	s_waitcnt lgkmcnt(0)
	v_mfma_f32_16x16x32_bf16 v[64:67], v[24:27], v[20:23], v[64:67]
	ds_read_b128 v[24:27], v94 offset:59264
	v_add_u32_e32 v205, v95, v97
	v_add_u32_e32 v214, v95, v101
	s_waitcnt lgkmcnt(0)
	v_mfma_f32_16x16x32_bf16 v[60:63], v[24:27], v[20:23], v[60:63]
	ds_read_b128 v[24:27], v172
	v_add_u32_e32 v206, v95, v103
	v_add_u32_e32 v207, v95, v106
	s_waitcnt lgkmcnt(0)
	v_mfma_f32_16x16x32_bf16 v[48:51], v[24:27], v[20:23], v[28:31]
	ds_read_b128 v[24:27], v173
	v_add_u32_e32 v208, v95, v108
	v_add_u32_e32 v210, v95, v107
	s_waitcnt lgkmcnt(0)
	v_mfma_f32_16x16x32_bf16 v[44:47], v[24:27], v[20:23], v[32:35]
	ds_read_b128 v[24:27], v174
	v_add_u32_e32 v212, v95, v105
	v_add_u32_e32 v213, v95, v104
	s_waitcnt lgkmcnt(0)
	v_mfma_f32_16x16x32_bf16 v[40:43], v[24:27], v[20:23], v[118:121]
	ds_read_b128 v[24:27], v175
	s_mov_b32 s8, 0xff61b1e6
	s_waitcnt lgkmcnt(0)
	v_mfma_f32_16x16x32_bf16 v[36:39], v[24:27], v[20:23], v[56:59]
	ds_read_b128 v[24:27], v176
	s_nop 1
	ds_read_b128 v[56:59], v94 offset:8640
	s_waitcnt lgkmcnt(1)
	v_mfma_f32_16x16x32_bf16 v[32:35], v[24:27], v[20:23], v[52:55]
	ds_read_b128 v[24:27], v177
	s_nop 1
	ds_read_b128 v[52:55], v179
	s_waitcnt lgkmcnt(1)
	v_mfma_f32_16x16x32_bf16 v[28:31], v[24:27], v[20:23], v[122:125]
	ds_read_b128 v[24:27], v178
	s_waitcnt lgkmcnt(0)
	v_mfma_f32_16x16x32_bf16 v[24:27], v[24:27], v[20:23], v[130:133]
	v_mfma_f32_16x16x32_bf16 v[20:23], v[52:55], v[20:23], v[134:137]
	ds_read_b128 v[52:55], v94 offset:192
	s_waitcnt vmcnt(4) lgkmcnt(0)
	v_mfma_f32_16x16x32_bf16 v[52:55], v[52:55], v[16:19], v[110:113]
	s_nop 2
	ds_read_b128 v[110:113], v94 offset:17088
	s_waitcnt lgkmcnt(0)
	v_mfma_f32_16x16x32_bf16 v[80:83], v[110:113], v[16:19], v[80:83]
	ds_read_b128 v[110:113], v94 offset:25536
	s_waitcnt lgkmcnt(0)
; #define LAS __attribute__((address_space(3)))
; #define MFMA16(a, b, c) __builtin_amdgcn_mfma_f32_16x16x32_bf16((a), (b), (c), 0, 0, 0)
; __device__ __forceinline__ void xattn_pair(LAS unsigned char* lds, int bh, size_t row_base, bf16* QO, const bf16* Kx, const bf16* VTx, int tid, const WsRef& wsr) {
;     ...
;         for (int kk = 0; kk < 8; ++kk)
; #pragma unroll
;             for (int n = 0; n < 16; ++n) { const bf16x8 kf = *(const LAS bf16x8*)(T + (n * 16 + fr) * LDX + kk * 32 + fq * 8); sx[n] = MFMA16(kf, qf[kk], sx[n]); }
	v_mfma_f32_16x16x32_bf16 v[76:79], v[110:113], v[16:19], v[76:79]
	ds_read_b128 v[110:113], v94 offset:33984
	s_waitcnt lgkmcnt(0)
	v_mfma_f32_16x16x32_bf16 v[72:75], v[110:113], v[16:19], v[72:75]
	ds_read_b128 v[110:113], v94 offset:42432
	s_waitcnt lgkmcnt(0)
	v_mfma_f32_16x16x32_bf16 v[68:71], v[110:113], v[16:19], v[68:71]
	ds_read_b128 v[110:113], v94 offset:50880
	s_waitcnt lgkmcnt(0)
	v_mfma_f32_16x16x32_bf16 v[64:67], v[110:113], v[16:19], v[64:67]
	ds_read_b128 v[110:113], v94 offset:59328
	s_waitcnt lgkmcnt(0)
	v_mfma_f32_16x16x32_bf16 v[60:63], v[110:113], v[16:19], v[60:63]
	ds_read_b128 v[110:113], v180
	s_waitcnt lgkmcnt(0)
	v_mfma_f32_16x16x32_bf16 v[48:51], v[110:113], v[16:19], v[48:51]
	ds_read_b128 v[110:113], v181
	s_waitcnt lgkmcnt(0)
	v_mfma_f32_16x16x32_bf16 v[44:47], v[110:113], v[16:19], v[44:47]
	ds_read_b128 v[110:113], v182
	s_waitcnt lgkmcnt(0)
	v_mfma_f32_16x16x32_bf16 v[110:113], v[110:113], v[16:19], v[40:43]
	s_nop 2
	ds_read_b128 v[40:43], v183
	v_mfma_f32_16x16x32_bf16 v[56:59], v[56:59], v[16:19], v[114:117]
	s_waitcnt lgkmcnt(0)
	v_mfma_f32_16x16x32_bf16 v[114:117], v[40:43], v[16:19], v[36:39]
	s_nop 2
	ds_read_b128 v[36:39], v184
	s_waitcnt lgkmcnt(0)
	v_mfma_f32_16x16x32_bf16 v[118:121], v[36:39], v[16:19], v[32:35]
	s_nop 2
	ds_read_b128 v[32:35], v185
	s_waitcnt lgkmcnt(0)
	v_mfma_f32_16x16x32_bf16 v[122:125], v[32:35], v[16:19], v[28:31]
	s_nop 2
	ds_read_b128 v[28:31], v186
	s_waitcnt lgkmcnt(0)
	v_mfma_f32_16x16x32_bf16 v[130:133], v[28:31], v[16:19], v[24:27]
	s_nop 2
	ds_read_b128 v[24:27], v187
	s_waitcnt lgkmcnt(0)
	v_mfma_f32_16x16x32_bf16 v[134:137], v[24:27], v[16:19], v[20:23]
	ds_read_b128 v[16:19], v94 offset:256
	s_waitcnt vmcnt(3) lgkmcnt(0)
	v_mfma_f32_16x16x32_bf16 v[52:55], v[16:19], v[12:15], v[52:55]
	ds_read_b128 v[16:19], v94 offset:8704
	s_waitcnt lgkmcnt(0)
	v_mfma_f32_16x16x32_bf16 v[56:59], v[16:19], v[12:15], v[56:59]
	ds_read_b128 v[16:19], v94 offset:17152
	s_waitcnt lgkmcnt(0)
	v_mfma_f32_16x16x32_bf16 v[80:83], v[16:19], v[12:15], v[80:83]
	ds_read_b128 v[16:19], v94 offset:25600
	s_waitcnt lgkmcnt(0)
	v_mfma_f32_16x16x32_bf16 v[76:79], v[16:19], v[12:15], v[76:79]
	ds_read_b128 v[16:19], v94 offset:34048
	s_waitcnt lgkmcnt(0)
	v_mfma_f32_16x16x32_bf16 v[72:75], v[16:19], v[12:15], v[72:75]
	ds_read_b128 v[16:19], v94 offset:42496
	s_waitcnt lgkmcnt(0)
	v_mfma_f32_16x16x32_bf16 v[68:71], v[16:19], v[12:15], v[68:71]
	ds_read_b128 v[16:19], v94 offset:50944
	s_waitcnt lgkmcnt(0)
	v_mfma_f32_16x16x32_bf16 v[64:67], v[16:19], v[12:15], v[64:67]
	ds_read_b128 v[16:19], v94 offset:59392
	s_waitcnt lgkmcnt(0)
	v_mfma_f32_16x16x32_bf16 v[60:63], v[16:19], v[12:15], v[60:63]
	ds_read_b128 v[16:19], v188
	s_waitcnt lgkmcnt(0)
	v_mfma_f32_16x16x32_bf16 v[40:43], v[16:19], v[12:15], v[48:51]
	ds_read_b128 v[16:19], v189
	s_nop 1
	ds_read_b128 v[48:51], v94 offset:8768
	s_waitcnt lgkmcnt(1)
	v_mfma_f32_16x16x32_bf16 v[36:39], v[16:19], v[12:15], v[44:47]
	ds_read_b128 v[16:19], v190
	s_nop 1
	ds_read_b128 v[44:47], v195
	s_waitcnt vmcnt(2) lgkmcnt(2)
	v_mfma_f32_16x16x32_bf16 v[48:51], v[48:51], v[8:11], v[56:59]
	s_nop 2
	ds_read_b128 v[56:59], v94 offset:25664
	s_waitcnt lgkmcnt(2)
	v_mfma_f32_16x16x32_bf16 v[32:35], v[16:19], v[12:15], v[110:113]
	ds_read_b128 v[16:19], v191
	s_waitcnt lgkmcnt(0)
	v_mfma_f32_16x16x32_bf16 v[28:31], v[16:19], v[12:15], v[114:117]
	ds_read_b128 v[16:19], v192
	s_waitcnt lgkmcnt(0)
	v_mfma_f32_16x16x32_bf16 v[24:27], v[16:19], v[12:15], v[118:121]
	ds_read_b128 v[16:19], v193
	s_waitcnt lgkmcnt(0)
	v_mfma_f32_16x16x32_bf16 v[20:23], v[16:19], v[12:15], v[122:125]
	ds_read_b128 v[16:19], v194
	s_waitcnt lgkmcnt(0)
	v_mfma_f32_16x16x32_bf16 v[16:19], v[16:19], v[12:15], v[130:133]
	v_mfma_f32_16x16x32_bf16 v[12:15], v[44:47], v[12:15], v[134:137]
	ds_read_b128 v[44:47], v94 offset:320
	v_mfma_f32_16x16x32_bf16 v[56:59], v[56:59], v[8:11], v[76:79]
	s_nop 2
	ds_read_b128 v[76:79], v94 offset:34112
	s_waitcnt lgkmcnt(1)
	v_mfma_f32_16x16x32_bf16 v[44:47], v[44:47], v[8:11], v[52:55]
	s_nop 2
	ds_read_b128 v[52:55], v94 offset:17216
	s_waitcnt lgkmcnt(1)
	v_mfma_f32_16x16x32_bf16 v[72:75], v[76:79], v[8:11], v[72:75]
	ds_read_b128 v[76:79], v94 offset:42560
	s_waitcnt lgkmcnt(0)
	v_mfma_f32_16x16x32_bf16 v[68:71], v[76:79], v[8:11], v[68:71]
	ds_read_b128 v[76:79], v94 offset:51008
	s_waitcnt lgkmcnt(0)
	v_mfma_f32_16x16x32_bf16 v[64:67], v[76:79], v[8:11], v[64:67]
	ds_read_b128 v[76:79], v94 offset:59456
	s_waitcnt lgkmcnt(0)
	v_mfma_f32_16x16x32_bf16 v[60:63], v[76:79], v[8:11], v[60:63]
	ds_read_b128 v[76:79], v199
	s_waitcnt lgkmcnt(0)
	v_mfma_f32_16x16x32_bf16 v[40:43], v[76:79], v[8:11], v[40:43]
	ds_read_b128 v[76:79], v196
	s_waitcnt lgkmcnt(0)
	v_mfma_f32_16x16x32_bf16 v[36:39], v[76:79], v[8:11], v[36:39]
	ds_read_b128 v[76:79], v197
	s_waitcnt lgkmcnt(0)
	v_mfma_f32_16x16x32_bf16 v[32:35], v[76:79], v[8:11], v[32:35]
	ds_read_b128 v[76:79], v198
	s_waitcnt lgkmcnt(0)
	v_mfma_f32_16x16x32_bf16 v[28:31], v[76:79], v[8:11], v[28:31]
	ds_read_b128 v[76:79], v200
	s_waitcnt lgkmcnt(0)
	v_mfma_f32_16x16x32_bf16 v[24:27], v[76:79], v[8:11], v[24:27]
	ds_read_b128 v[76:79], v201
	s_waitcnt lgkmcnt(0)
	v_mfma_f32_16x16x32_bf16 v[20:23], v[76:79], v[8:11], v[20:23]
	ds_read_b128 v[76:79], v202
	s_waitcnt lgkmcnt(0)
	v_mfma_f32_16x16x32_bf16 v[16:19], v[76:79], v[8:11], v[16:19]
	ds_read_b128 v[76:79], v203
	v_mfma_f32_16x16x32_bf16 v[52:55], v[52:55], v[8:11], v[80:83]
	s_waitcnt lgkmcnt(0)
	v_mfma_f32_16x16x32_bf16 v[8:11], v[76:79], v[8:11], v[12:15]
	s_nop 2
	ds_read_b128 v[12:15], v94 offset:384
	s_waitcnt vmcnt(1) lgkmcnt(0)
; #define LAS __attribute__((address_space(3)))
; #define MFMA16(a, b, c) __builtin_amdgcn_mfma_f32_16x16x32_bf16((a), (b), (c), 0, 0, 0)
; __device__ __forceinline__ void xattn_softmax(f32x4 (&s)[16], bf16x8 (&pf)[8], float& rinv) {
;     ...
;     for (int n = 0; n < 16; ++n) mx = fmaxf(mx, fmaxf(fmaxf(s[n][0], s[n][1]), fmaxf(s[n][2], s[n][3])));
;     mx = fmaxf(mx, __shfl_xor(mx, 16)); mx = fmaxf(mx, __shfl_xor(mx, 32));
; __device__ __forceinline__ void xattn_pair(LAS unsigned char* lds, int bh, size_t row_base, bf16* QO, const bf16* Kx, const bf16* VTx, int tid, const WsRef& wsr) {
;     ...
;         for (int kk = 0; kk < 8; ++kk)
; #pragma unroll
;             for (int n = 0; n < 16; ++n) { const bf16x8 kf = *(const LAS bf16x8*)(T + (n * 16 + fr) * LDX + kk * 32 + fq * 8); sx[n] = MFMA16(kf, qf[kk], sx[n]); }
	v_mfma_f32_16x16x32_bf16 v[12:15], v[12:15], v[4:7], v[44:47]
	s_nop 2
	ds_read_b128 v[44:47], v94 offset:8832
	s_waitcnt lgkmcnt(0)
	v_mfma_f32_16x16x32_bf16 v[44:47], v[44:47], v[4:7], v[48:51]
	s_nop 2
	ds_read_b128 v[48:51], v94 offset:17280
	s_waitcnt lgkmcnt(0)
	v_mfma_f32_16x16x32_bf16 v[48:51], v[48:51], v[4:7], v[52:55]
	s_nop 2
	ds_read_b128 v[52:55], v94 offset:25728
	s_waitcnt lgkmcnt(0)
	v_mfma_f32_16x16x32_bf16 v[76:79], v[52:55], v[4:7], v[56:59]
	ds_read_b128 v[52:55], v94 offset:34176
	s_waitcnt lgkmcnt(0)
	v_mfma_f32_16x16x32_bf16 v[72:75], v[52:55], v[4:7], v[72:75]
	ds_read_b128 v[52:55], v94 offset:42624
	s_waitcnt lgkmcnt(0)
	v_mfma_f32_16x16x32_bf16 v[68:71], v[52:55], v[4:7], v[68:71]
	ds_read_b128 v[52:55], v94 offset:51072
	s_waitcnt lgkmcnt(0)
	v_mfma_f32_16x16x32_bf16 v[64:67], v[52:55], v[4:7], v[64:67]
	ds_read_b128 v[52:55], v94 offset:59520
	s_waitcnt lgkmcnt(0)
	v_mfma_f32_16x16x32_bf16 v[80:83], v[52:55], v[4:7], v[60:63]
	ds_read_b128 v[52:55], v209
	s_waitcnt lgkmcnt(0)
	v_mfma_f32_16x16x32_bf16 v[110:113], v[52:55], v[4:7], v[40:43]
	s_nop 2
	ds_read_b128 v[40:43], v211
	s_waitcnt lgkmcnt(0)
	v_mfma_f32_16x16x32_bf16 v[114:117], v[40:43], v[4:7], v[36:39]
	s_nop 2
	ds_read_b128 v[36:39], v215
	s_waitcnt lgkmcnt(0)
	v_mfma_f32_16x16x32_bf16 v[118:121], v[36:39], v[4:7], v[32:35]
	s_nop 2
	ds_read_b128 v[32:35], v216
	s_waitcnt lgkmcnt(0)
	v_mfma_f32_16x16x32_bf16 v[122:125], v[32:35], v[4:7], v[28:31]
	s_nop 2
	ds_read_b128 v[28:31], v217
	s_waitcnt lgkmcnt(0)
	v_mfma_f32_16x16x32_bf16 v[130:133], v[28:31], v[4:7], v[24:27]
	s_nop 2
	ds_read_b128 v[24:27], v218
	s_waitcnt lgkmcnt(0)
	v_mfma_f32_16x16x32_bf16 v[134:137], v[24:27], v[4:7], v[20:23]
	s_nop 2
	ds_read_b128 v[20:23], v219
	s_waitcnt lgkmcnt(0)
	v_mfma_f32_16x16x32_bf16 v[138:141], v[20:23], v[4:7], v[16:19]
	s_nop 2
	ds_read_b128 v[16:19], v220
	s_waitcnt lgkmcnt(0)
	v_mfma_f32_16x16x32_bf16 v[142:145], v[16:19], v[4:7], v[8:11]
	ds_read_b128 v[4:7], v94 offset:448
	s_waitcnt vmcnt(0) lgkmcnt(0)
	v_mfma_f32_16x16x32_bf16 v[60:63], v[4:7], v[0:3], v[12:15]
	ds_read_b128 v[4:7], v94 offset:8896
	s_waitcnt lgkmcnt(0)
	v_mfma_f32_16x16x32_bf16 v[56:59], v[4:7], v[0:3], v[44:47]
	ds_read_b128 v[4:7], v94 offset:17344
	s_waitcnt lgkmcnt(0)
	v_mfma_f32_16x16x32_bf16 v[52:55], v[4:7], v[0:3], v[48:51]
	ds_read_b128 v[4:7], v94 offset:25792
	s_waitcnt lgkmcnt(0)
	v_mfma_f32_16x16x32_bf16 v[48:51], v[4:7], v[0:3], v[76:79]
	ds_read_b128 v[4:7], v94 offset:34240
	s_waitcnt lgkmcnt(0)
	v_mfma_f32_16x16x32_bf16 v[44:47], v[4:7], v[0:3], v[72:75]
	ds_read_b128 v[4:7], v94 offset:42688
	s_waitcnt lgkmcnt(0)
	v_mfma_f32_16x16x32_bf16 v[40:43], v[4:7], v[0:3], v[68:71]
	ds_read_b128 v[4:7], v94 offset:51136
	s_waitcnt lgkmcnt(0)
	v_mfma_f32_16x16x32_bf16 v[36:39], v[4:7], v[0:3], v[64:67]
	ds_read_b128 v[4:7], v94 offset:59584
	s_nop 1
	ds_read_b128 v[64:67], v214
	s_waitcnt lgkmcnt(1)
	v_mfma_f32_16x16x32_bf16 v[32:35], v[4:7], v[0:3], v[80:83]
	ds_read_b128 v[4:7], v205
	s_waitcnt lgkmcnt(0)
	v_mfma_f32_16x16x32_bf16 v[28:31], v[4:7], v[0:3], v[110:113]
	ds_read_b128 v[4:7], v206
	s_waitcnt lgkmcnt(0)
	v_mfma_f32_16x16x32_bf16 v[24:27], v[4:7], v[0:3], v[114:117]
	ds_read_b128 v[4:7], v207
	s_waitcnt lgkmcnt(0)
	v_mfma_f32_16x16x32_bf16 v[20:23], v[4:7], v[0:3], v[118:121]
	ds_read_b128 v[4:7], v208
	s_waitcnt lgkmcnt(0)
	v_mfma_f32_16x16x32_bf16 v[16:19], v[4:7], v[0:3], v[122:125]
	ds_read_b128 v[4:7], v210
	s_waitcnt lgkmcnt(0)
	v_mfma_f32_16x16x32_bf16 v[12:15], v[4:7], v[0:3], v[130:133]
	ds_read_b128 v[4:7], v212
	s_waitcnt lgkmcnt(0)
	v_mfma_f32_16x16x32_bf16 v[8:11], v[4:7], v[0:3], v[134:137]
	ds_read_b128 v[4:7], v213
	s_waitcnt lgkmcnt(0)
	v_mfma_f32_16x16x32_bf16 v[4:7], v[4:7], v[0:3], v[138:141]
	v_mfma_f32_16x16x32_bf16 v[0:3], v[64:67], v[0:3], v[142:145]
	v_max_f32_e32 v64, v63, v63
	v_max_f32_e32 v65, v62, v62
	v_max_f32_e32 v64, v65, v64
	v_max_f32_e32 v65, v59, v59
	v_max_f32_e32 v66, v58, v58
	v_max_f32_e32 v65, v66, v65
	v_max3_f32 v64, v60, v61, v64
	v_max3_f32 v65, v56, v57, v65
	v_max3_f32 v64, v64, s8, v65
	v_max_f32_e32 v65, v55, v55
	v_max_f32_e32 v66, v54, v54
	v_max_f32_e32 v65, v66, v65
	v_max_f32_e32 v66, v51, v51
	v_max_f32_e32 v67, v50, v50
	v_max_f32_e32 v66, v67, v66
	v_max3_f32 v65, v52, v53, v65
	v_max3_f32 v66, v48, v49, v66
	v_max3_f32 v64, v64, v65, v66
	v_max_f32_e32 v65, v47, v47
	v_max_f32_e32 v66, v46, v46
	v_max_f32_e32 v65, v66, v65
	v_max_f32_e32 v66, v43, v43
	v_max_f32_e32 v67, v42, v42
	v_max_f32_e32 v66, v67, v66
	v_max3_f32 v65, v44, v45, v65
	v_max3_f32 v66, v40, v41, v66
	v_max3_f32 v64, v64, v65, v66
	v_max_f32_e32 v65, v39, v39
	v_max_f32_e32 v66, v38, v38
	v_max_f32_e32 v65, v66, v65
	v_max_f32_e32 v66, v35, v35
	v_max_f32_e32 v67, v34, v34
	v_max_f32_e32 v66, v67, v66
	v_max3_f32 v65, v36, v37, v65
	v_max3_f32 v66, v32, v33, v66
	v_max3_f32 v64, v64, v65, v66
	v_max_f32_e32 v65, v31, v31
	v_max_f32_e32 v66, v30, v30
	v_max_f32_e32 v65, v66, v65
	v_max_f32_e32 v66, v27, v27
	v_max_f32_e32 v67, v26, v26
	v_max_f32_e32 v66, v67, v66
	v_max3_f32 v65, v28, v29, v65
	v_max3_f32 v66, v24, v25, v66
	v_max3_f32 v64, v64, v65, v66
	v_max_f32_e32 v65, v23, v23
	v_max_f32_e32 v66, v22, v22
	v_max_f32_e32 v65, v66, v65
	v_max_f32_e32 v66, v19, v19
	v_max_f32_e32 v67, v18, v18
	v_max_f32_e32 v66, v67, v66
	v_max3_f32 v65, v20, v21, v65
	v_max3_f32 v66, v16, v17, v66
	v_max3_f32 v64, v64, v65, v66
	v_max_f32_e32 v65, v15, v15
	v_max_f32_e32 v66, v14, v14
	v_max_f32_e32 v65, v66, v65
	v_max_f32_e32 v66, v11, v11
	v_max_f32_e32 v67, v10, v10
	v_max_f32_e32 v66, v67, v66
	v_max3_f32 v65, v12, v13, v65
	v_max3_f32 v66, v8, v9, v66
	v_max3_f32 v64, v64, v65, v66
	v_max_f32_e32 v65, v7, v7
	v_max_f32_e32 v66, v6, v6
	v_max_f32_e32 v65, v66, v65
	v_max_f32_e32 v66, v3, v3
	v_max_f32_e32 v67, v2, v2
	v_max_f32_e32 v66, v67, v66
	v_max3_f32 v65, v4, v5, v65
	v_max3_f32 v66, v0, v1, v66
	v_max3_f32 v64, v64, v65, v66
	v_mbcnt_lo_u32_b32 v65, -1, 0
	v_mbcnt_hi_u32_b32 v65, -1, v65
	v_and_b32_e32 v67, 64, v65
	v_xor_b32_e32 v66, 16, v65
	v_add_u32_e32 v67, 64, v67
	v_cmp_lt_i32_e32 vcc, v66, v67
	s_nop 1
	v_cndmask_b32_e32 v66, v65, v66, vcc
	v_lshlrev_b32_e32 v155, 2, v66
	ds_bpermute_b32 v66, v155, v64
	s_waitcnt lgkmcnt(0)
; __device__ __forceinline__ float fexp2(float x) { return __builtin_amdgcn_exp2f(x); }
; __device__ __forceinline__ void xattn_softmax(f32x4 (&s)[16], bf16x8 (&pf)[8], float& rinv) {
;     ...
;     mx = fmaxf(mx, __shfl_xor(mx, 16)); mx = fmaxf(mx, __shfl_xor(mx, 32));
;     const float sc = 0.0625f * LOG2E; float sum = 0.f;
; #pragma unroll
;     for (int n = 0; n < 16; ++n)
; #pragma unroll
;         for (int r = 0; r < 4; ++r) { const float p = fexp2((s[n][r] - mx) * sc); s[n][r] = p; sum += p; }
	v_max_f32_e32 v66, v66, v66
	v_max_f32_e32 v66, v64, v66
	v_xor_b32_e32 v64, 32, v65
	v_cmp_lt_i32_e32 vcc, v64, v67
	s_nop 1
	v_cndmask_b32_e32 v64, v65, v64, vcc
	v_lshlrev_b32_e32 v64, 2, v64
	ds_bpermute_b32 v65, v64, v66
	s_waitcnt lgkmcnt(0)
	v_max_f32_e32 v65, v65, v65
	v_max_f32_e32 v147, v66, v65
	v_sub_f32_e32 v61, v61, v147
	v_sub_f32_e32 v60, v60, v147
	v_mul_f32_e32 v61, 0x3db8aa3b, v61
	v_mul_f32_e32 v60, 0x3db8aa3b, v60
	v_exp_f32_e32 v136, v61
	v_sub_f32_e32 v61, v62, v147
	v_exp_f32_e32 v133, v60
	v_mul_f32_e32 v61, 0x3db8aa3b, v61
	v_exp_f32_e32 v140, v61
	v_sub_f32_e32 v61, v63, v147
	v_sub_f32_e32 v57, v57, v147
	v_mul_f32_e32 v61, 0x3db8aa3b, v61
	v_sub_f32_e32 v56, v56, v147
	v_mul_f32_e32 v57, 0x3db8aa3b, v57
	v_exp_f32_e32 v144, v61
	v_mul_f32_e32 v56, 0x3db8aa3b, v56
	v_exp_f32_e32 v150, v57
	v_sub_f32_e32 v57, v58, v147
	v_add_f32_e32 v60, 0, v133
	v_exp_f32_e32 v149, v56
	v_mul_f32_e32 v57, 0x3db8aa3b, v57
	v_add_f32_e32 v60, v136, v60
	v_exp_f32_e32 v151, v57
	v_sub_f32_e32 v57, v59, v147
	v_sub_f32_e32 v53, v53, v147
	v_add_f32_e32 v60, v140, v60
	v_mul_f32_e32 v57, 0x3db8aa3b, v57
	v_sub_f32_e32 v52, v52, v147
	v_mul_f32_e32 v53, 0x3db8aa3b, v53
	v_add_f32_e32 v60, v144, v60
	v_exp_f32_e32 v152, v57
	v_mul_f32_e32 v52, 0x3db8aa3b, v52
	v_exp_f32_e32 v123, v53
	v_sub_f32_e32 v53, v54, v147
	v_add_f32_e32 v56, v149, v60
	v_exp_f32_e32 v118, v52
	v_mul_f32_e32 v53, 0x3db8aa3b, v53
	v_add_f32_e32 v56, v150, v56
	v_exp_f32_e32 v127, v53
	v_sub_f32_e32 v53, v55, v147
	v_sub_f32_e32 v49, v49, v147
	v_add_f32_e32 v56, v151, v56
	v_mul_f32_e32 v53, 0x3db8aa3b, v53
	v_sub_f32_e32 v48, v48, v147
	v_mul_f32_e32 v49, 0x3db8aa3b, v49
	v_add_f32_e32 v56, v152, v56
	v_exp_f32_e32 v132, v53
	v_mul_f32_e32 v48, 0x3db8aa3b, v48
	v_exp_f32_e32 v143, v49
	v_sub_f32_e32 v49, v50, v147
	v_add_f32_e32 v52, v118, v56
	v_exp_f32_e32 v139, v48
	v_mul_f32_e32 v49, 0x3db8aa3b, v49
	v_add_f32_e32 v52, v123, v52
	v_exp_f32_e32 v146, v49
	v_sub_f32_e32 v49, v51, v147
	v_sub_f32_e32 v45, v45, v147
	v_add_f32_e32 v52, v127, v52
	v_mul_f32_e32 v49, 0x3db8aa3b, v49
	v_sub_f32_e32 v44, v44, v147
	v_mul_f32_e32 v45, 0x3db8aa3b, v45
	v_add_f32_e32 v52, v132, v52
	v_exp_f32_e32 v148, v49
	v_mul_f32_e32 v44, 0x3db8aa3b, v44
	v_exp_f32_e32 v114, v45
	v_sub_f32_e32 v45, v46, v147
	v_add_f32_e32 v48, v139, v52
	v_exp_f32_e32 v111, v44
	v_mul_f32_e32 v45, 0x3db8aa3b, v45
	v_add_f32_e32 v48, v143, v48
	v_exp_f32_e32 v117, v45
	v_sub_f32_e32 v45, v47, v147
	v_sub_f32_e32 v41, v41, v147
	v_add_f32_e32 v48, v146, v48
	v_mul_f32_e32 v45, 0x3db8aa3b, v45
	v_sub_f32_e32 v40, v40, v147
	v_mul_f32_e32 v41, 0x3db8aa3b, v41
	v_add_f32_e32 v48, v148, v48
	v_exp_f32_e32 v122, v45
	v_mul_f32_e32 v40, 0x3db8aa3b, v40
	v_exp_f32_e32 v135, v41
	v_sub_f32_e32 v41, v42, v147
	v_add_f32_e32 v44, v111, v48
	v_exp_f32_e32 v130, v40
	v_mul_f32_e32 v41, 0x3db8aa3b, v41
	v_add_f32_e32 v44, v114, v44
	v_exp_f32_e32 v138, v41
	v_sub_f32_e32 v41, v43, v147
	v_sub_f32_e32 v37, v37, v147
	v_add_f32_e32 v44, v117, v44
	v_mul_f32_e32 v41, 0x3db8aa3b, v41
	v_sub_f32_e32 v36, v36, v147
	v_mul_f32_e32 v37, 0x3db8aa3b, v37
	v_add_f32_e32 v44, v122, v44
	v_exp_f32_e32 v142, v41
	v_mul_f32_e32 v36, 0x3db8aa3b, v36
	v_exp_f32_e32 v102, v37
	v_sub_f32_e32 v37, v38, v147
	v_add_f32_e32 v40, v130, v44
	v_exp_f32_e32 v83, v36
	v_mul_f32_e32 v37, 0x3db8aa3b, v37
	v_add_f32_e32 v40, v135, v40
	v_exp_f32_e32 v110, v37
	v_sub_f32_e32 v37, v39, v147
	v_sub_f32_e32 v33, v33, v147
	v_add_f32_e32 v40, v138, v40
	v_mul_f32_e32 v37, 0x3db8aa3b, v37
	v_sub_f32_e32 v32, v32, v147
	v_mul_f32_e32 v33, 0x3db8aa3b, v33
	v_add_f32_e32 v40, v142, v40
	v_exp_f32_e32 v113, v37
	v_mul_f32_e32 v32, 0x3db8aa3b, v32
	v_exp_f32_e32 v125, v33
	v_sub_f32_e32 v33, v34, v147
	v_add_f32_e32 v36, v83, v40
	v_exp_f32_e32 v120, v32
	v_mul_f32_e32 v33, 0x3db8aa3b, v33
	v_add_f32_e32 v36, v102, v36
	v_exp_f32_e32 v129, v33
	v_sub_f32_e32 v33, v35, v147
	v_sub_f32_e32 v29, v29, v147
	v_add_f32_e32 v36, v110, v36
	v_mul_f32_e32 v33, 0x3db8aa3b, v33
	v_sub_f32_e32 v28, v28, v147
	v_mul_f32_e32 v29, 0x3db8aa3b, v29
	v_add_f32_e32 v36, v113, v36
	v_exp_f32_e32 v134, v33
	v_mul_f32_e32 v28, 0x3db8aa3b, v28
	v_exp_f32_e32 v80, v29
	v_sub_f32_e32 v29, v30, v147
	v_add_f32_e32 v32, v120, v36
	v_exp_f32_e32 v78, v28
	v_mul_f32_e32 v29, 0x3db8aa3b, v29
	v_add_f32_e32 v32, v125, v32
	v_exp_f32_e32 v82, v29
	v_sub_f32_e32 v29, v31, v147
	v_sub_f32_e32 v25, v25, v147
	v_add_f32_e32 v32, v129, v32
	v_mul_f32_e32 v29, 0x3db8aa3b, v29
	v_sub_f32_e32 v24, v24, v147
	v_mul_f32_e32 v25, 0x3db8aa3b, v25
	v_add_f32_e32 v32, v134, v32
	v_exp_f32_e32 v100, v29
	v_mul_f32_e32 v24, 0x3db8aa3b, v24
	v_exp_f32_e32 v115, v25
	v_sub_f32_e32 v25, v26, v147
	v_add_f32_e32 v28, v78, v32
	v_exp_f32_e32 v112, v24
	v_mul_f32_e32 v25, 0x3db8aa3b, v25
	v_add_f32_e32 v28, v80, v28
	v_exp_f32_e32 v119, v25
	v_sub_f32_e32 v25, v27, v147
	v_sub_f32_e32 v21, v21, v147
	v_add_f32_e32 v28, v82, v28
	v_mul_f32_e32 v25, 0x3db8aa3b, v25
	v_sub_f32_e32 v20, v20, v147
	v_mul_f32_e32 v21, 0x3db8aa3b, v21
	v_add_f32_e32 v28, v100, v28
	v_exp_f32_e32 v124, v25
	v_mul_f32_e32 v20, 0x3db8aa3b, v20
	v_exp_f32_e32 v69, v21
	v_sub_f32_e32 v21, v22, v147
	v_add_f32_e32 v24, v112, v28
	v_exp_f32_e32 v66, v20
	v_mul_f32_e32 v21, 0x3db8aa3b, v21
	v_add_f32_e32 v24, v115, v24
	v_exp_f32_e32 v71, v21
	v_sub_f32_e32 v21, v23, v147
	v_sub_f32_e32 v17, v17, v147
	v_add_f32_e32 v24, v119, v24
	v_mul_f32_e32 v21, 0x3db8aa3b, v21
	v_sub_f32_e32 v16, v16, v147
	v_mul_f32_e32 v17, 0x3db8aa3b, v17
	v_add_f32_e32 v24, v124, v24
	v_exp_f32_e32 v72, v21
	v_mul_f32_e32 v16, 0x3db8aa3b, v16
; #define LAS __attribute__((address_space(3)))
; __device__ __forceinline__ float fexp2(float x) { return __builtin_amdgcn_exp2f(x); }
; #define MFMA16(a, b, c) __builtin_amdgcn_mfma_f32_16x16x32_bf16((a), (b), (c), 0, 0, 0)
; __device__ __forceinline__ void xattn_softmax(f32x4 (&s)[16], bf16x8 (&pf)[8], float& rinv) {
;     ...
;         for (int r = 0; r < 4; ++r) { const float p = fexp2((s[n][r] - mx) * sc); s[n][r] = p; sum += p; }
;     sum += __shfl_xor(sum, 16); sum += __shfl_xor(sum, 32);
; __device__ __forceinline__ void xattn_pair(LAS unsigned char* lds, int bh, size_t row_base, bf16* QO, const bf16* Kx, const bf16* VTx, int tid, const WsRef& wsr) {
;     ...
;         for (int kk = 0; kk < 8; ++kk) qf[kk] = *(const bf16x8*)(qp + kk * 32 + fq * 8);
;         f32x4 sx[16];
; #pragma unroll
;         for (int n = 0; n < 16; ++n) sx[n] = (f32x4){0.f, 0.f, 0.f, 0.f};
; #pragma unroll
;         for (int kk = 0; kk < 8; ++kk)
; #pragma unroll
;             for (int n = 0; n < 16; ++n) { const bf16x8 kf = *(const LAS bf16x8*)(T + (n * 16 + fr) * LDX + kk * 32 + fq * 8); sx[n] = MFMA16(kf, qf[kk], sx[n]); }
	v_exp_f32_e32 v79, v17
	v_sub_f32_e32 v17, v18, v147
	v_add_f32_e32 v20, v66, v24
	v_exp_f32_e32 v77, v16
	v_mul_f32_e32 v17, 0x3db8aa3b, v17
	v_add_f32_e32 v20, v69, v20
	v_exp_f32_e32 v81, v17
	v_sub_f32_e32 v17, v19, v147
	v_sub_f32_e32 v13, v13, v147
	v_add_f32_e32 v20, v71, v20
	v_mul_f32_e32 v17, 0x3db8aa3b, v17
	v_sub_f32_e32 v12, v12, v147
	v_mul_f32_e32 v13, 0x3db8aa3b, v13
	v_add_f32_e32 v20, v72, v20
	v_exp_f32_e32 v95, v17
	v_mul_f32_e32 v12, 0x3db8aa3b, v12
	v_exp_f32_e32 v68, v13
	v_sub_f32_e32 v13, v14, v147
	v_add_f32_e32 v16, v77, v20
	v_exp_f32_e32 v65, v12
	v_mul_f32_e32 v13, 0x3db8aa3b, v13
	v_add_f32_e32 v16, v79, v16
	v_exp_f32_e32 v67, v13
	v_sub_f32_e32 v13, v15, v147
	v_sub_f32_e32 v9, v9, v147
	v_add_f32_e32 v16, v81, v16
	v_mul_f32_e32 v13, 0x3db8aa3b, v13
	v_sub_f32_e32 v8, v8, v147
	v_mul_f32_e32 v9, 0x3db8aa3b, v9
	v_add_f32_e32 v16, v95, v16
	v_exp_f32_e32 v70, v13
	v_mul_f32_e32 v8, 0x3db8aa3b, v8
	v_exp_f32_e32 v76, v9
	v_sub_f32_e32 v9, v10, v147
	v_add_f32_e32 v12, v65, v16
	v_exp_f32_e32 v74, v8
	v_mul_f32_e32 v9, 0x3db8aa3b, v9
	v_add_f32_e32 v12, v68, v12
	v_exp_f32_e32 v73, v9
	v_sub_f32_e32 v9, v11, v147
	v_sub_f32_e32 v5, v5, v147
	v_add_f32_e32 v12, v67, v12
	v_mul_f32_e32 v9, 0x3db8aa3b, v9
	v_sub_f32_e32 v4, v4, v147
	v_mul_f32_e32 v5, 0x3db8aa3b, v5
	v_add_f32_e32 v12, v70, v12
	v_exp_f32_e32 v75, v9
	v_mul_f32_e32 v4, 0x3db8aa3b, v4
	v_exp_f32_e32 v121, v5
	v_sub_f32_e32 v5, v6, v147
	v_add_f32_e32 v8, v74, v12
	v_exp_f32_e32 v116, v4
	v_mul_f32_e32 v5, 0x3db8aa3b, v5
	v_add_f32_e32 v8, v76, v8
	v_exp_f32_e32 v126, v5
	v_sub_f32_e32 v5, v7, v147
	v_sub_f32_e32 v1, v1, v147
	v_add_f32_e32 v8, v73, v8
	v_mul_f32_e32 v5, 0x3db8aa3b, v5
	v_sub_f32_e32 v0, v0, v147
	v_mul_f32_e32 v1, 0x3db8aa3b, v1
	v_add_f32_e32 v8, v75, v8
	v_exp_f32_e32 v131, v5
	v_mul_f32_e32 v0, 0x3db8aa3b, v0
	v_exp_f32_e32 v141, v1
	v_sub_f32_e32 v1, v2, v147
	v_add_f32_e32 v4, v116, v8
	v_exp_f32_e32 v137, v0
	v_mul_f32_e32 v1, 0x3db8aa3b, v1
	v_add_f32_e32 v4, v121, v4
	v_exp_f32_e32 v145, v1
	v_sub_f32_e32 v1, v3, v147
	v_add_f32_e32 v4, v126, v4
	v_mul_f32_e32 v1, 0x3db8aa3b, v1
	v_add_f32_e32 v4, v131, v4
	v_exp_f32_e32 v147, v1
	v_add_f32_e32 v0, v137, v4
	v_add_f32_e32 v0, v141, v0
	v_add_f32_e32 v0, v145, v0
	v_add_f32_e32 v153, v147, v0
	ds_bpermute_b32 v154, v155, v153
	v_lshl_add_u64 v[0:1], v[98:99], 0, v[86:87]
	global_load_dwordx4 v[28:31], v[0:1], off
	global_load_dwordx4 v[24:27], v[0:1], off offset:64
	global_load_dwordx4 v[20:23], v[0:1], off offset:128
	global_load_dwordx4 v[16:19], v[0:1], off offset:192
	global_load_dwordx4 v[12:15], v[0:1], off offset:256
	global_load_dwordx4 v[8:11], v[0:1], off offset:320
	global_load_dwordx4 v[4:7], v[0:1], off offset:384
	s_nop 0
	global_load_dwordx4 v[0:3], v[0:1], off offset:448
	ds_read_b128 v[32:35], v94
	s_waitcnt vmcnt(7) lgkmcnt(0)
	v_mfma_f32_16x16x32_bf16 v[44:47], v[32:35], v[28:31], 0
	ds_read_b128 v[32:35], v94 offset:8448
	s_waitcnt lgkmcnt(0)
	v_mfma_f32_16x16x32_bf16 v[48:51], v[32:35], v[28:31], 0
	ds_read_b128 v[32:35], v94 offset:16896
	s_waitcnt lgkmcnt(0)
	v_mfma_f32_16x16x32_bf16 v[52:55], v[32:35], v[28:31], 0
	ds_read_b128 v[32:35], v94 offset:25344
	s_waitcnt lgkmcnt(0)
	v_mfma_f32_16x16x32_bf16 v[56:59], v[32:35], v[28:31], 0
	ds_read_b128 v[32:35], v94 offset:33792
	s_waitcnt lgkmcnt(0)
	v_mfma_f32_16x16x32_bf16 v[60:63], v[32:35], v[28:31], 0
	ds_read_b128 v[32:35], v94 offset:42240
	s_waitcnt lgkmcnt(0)
	v_mfma_f32_16x16x32_bf16 v[222:225], v[32:35], v[28:31], 0
	ds_read_b128 v[32:35], v94 offset:50688
	s_waitcnt lgkmcnt(0)
	v_mfma_f32_16x16x32_bf16 v[226:229], v[32:35], v[28:31], 0
	ds_read_b128 v[32:35], v94 offset:59136
	s_waitcnt lgkmcnt(0)
	v_mfma_f32_16x16x32_bf16 v[230:233], v[32:35], v[28:31], 0
	ds_read_b128 v[32:35], v156
	s_waitcnt lgkmcnt(0)
	v_mfma_f32_16x16x32_bf16 v[234:237], v[32:35], v[28:31], 0
	ds_read_b128 v[32:35], v157
	s_waitcnt lgkmcnt(0)
	v_mfma_f32_16x16x32_bf16 v[238:241], v[32:35], v[28:31], 0
	ds_read_b128 v[32:35], v158
	s_waitcnt lgkmcnt(0)
	v_mfma_f32_16x16x32_bf16 v[242:245], v[32:35], v[28:31], 0
	ds_read_b128 v[32:35], v159
	s_waitcnt lgkmcnt(0)
	v_mfma_f32_16x16x32_bf16 v[156:159], v[32:35], v[28:31], 0
	ds_read_b128 v[32:35], v160
	s_waitcnt lgkmcnt(0)
	v_mfma_f32_16x16x32_bf16 v[40:43], v[32:35], v[28:31], 0
	ds_read_b128 v[32:35], v161
	s_waitcnt lgkmcnt(0)
	v_mfma_f32_16x16x32_bf16 v[36:39], v[32:35], v[28:31], 0
	ds_read_b128 v[32:35], v162
	ds_read_b128 v[160:163], v163
	s_waitcnt lgkmcnt(1)
	v_mfma_f32_16x16x32_bf16 v[32:35], v[32:35], v[28:31], 0
	s_waitcnt lgkmcnt(0)
	v_mfma_f32_16x16x32_bf16 v[28:31], v[160:163], v[28:31], 0
	ds_read_b128 v[160:163], v94 offset:64
	s_waitcnt vmcnt(6) lgkmcnt(0)
	v_mfma_f32_16x16x32_bf16 v[44:47], v[160:163], v[24:27], v[44:47]
	ds_read_b128 v[160:163], v94 offset:8512
	s_waitcnt lgkmcnt(0)
	v_mfma_f32_16x16x32_bf16 v[48:51], v[160:163], v[24:27], v[48:51]
	ds_read_b128 v[160:163], v94 offset:16960
	s_waitcnt lgkmcnt(0)
	v_mfma_f32_16x16x32_bf16 v[52:55], v[160:163], v[24:27], v[52:55]
	ds_read_b128 v[160:163], v94 offset:25408
	s_waitcnt lgkmcnt(0)
	v_mfma_f32_16x16x32_bf16 v[56:59], v[160:163], v[24:27], v[56:59]
	ds_read_b128 v[160:163], v94 offset:33856
	s_waitcnt lgkmcnt(0)
	v_mfma_f32_16x16x32_bf16 v[60:63], v[160:163], v[24:27], v[60:63]
	ds_read_b128 v[160:163], v94 offset:42304
	s_waitcnt lgkmcnt(0)
	v_mfma_f32_16x16x32_bf16 v[160:163], v[160:163], v[24:27], v[222:225]
	s_nop 2
	ds_read_b128 v[222:225], v94 offset:50752
	s_waitcnt lgkmcnt(0)
	v_mfma_f32_16x16x32_bf16 v[222:225], v[222:225], v[24:27], v[226:229]
	s_nop 2
	ds_read_b128 v[226:229], v94 offset:59200
	s_waitcnt lgkmcnt(0)
; #define LAS __attribute__((address_space(3)))
; #define MFMA16(a, b, c) __builtin_amdgcn_mfma_f32_16x16x32_bf16((a), (b), (c), 0, 0, 0)
; __device__ __forceinline__ void xattn_pair(LAS unsigned char* lds, int bh, size_t row_base, bf16* QO, const bf16* Kx, const bf16* VTx, int tid, const WsRef& wsr) {
;     ...
;         for (int kk = 0; kk < 8; ++kk)
; #pragma unroll
;             for (int n = 0; n < 16; ++n) { const bf16x8 kf = *(const LAS bf16x8*)(T + (n * 16 + fr) * LDX + kk * 32 + fq * 8); sx[n] = MFMA16(kf, qf[kk], sx[n]); }
	v_mfma_f32_16x16x32_bf16 v[226:229], v[226:229], v[24:27], v[230:233]
	s_nop 2
	ds_read_b128 v[230:233], v164
	s_waitcnt lgkmcnt(0)
	v_mfma_f32_16x16x32_bf16 v[230:233], v[230:233], v[24:27], v[234:237]
	s_nop 2
	ds_read_b128 v[234:237], v165
	s_waitcnt lgkmcnt(0)
	v_mfma_f32_16x16x32_bf16 v[234:237], v[234:237], v[24:27], v[238:241]
	s_nop 2
	ds_read_b128 v[238:241], v166
	ds_read_b128 v[164:167], v167
	s_waitcnt lgkmcnt(0)
	v_mfma_f32_16x16x32_bf16 v[156:159], v[164:167], v[24:27], v[156:159]
	ds_read_b128 v[164:167], v168
	s_waitcnt lgkmcnt(0)
	v_mfma_f32_16x16x32_bf16 v[40:43], v[164:167], v[24:27], v[40:43]
	ds_read_b128 v[164:167], v169
	s_waitcnt lgkmcnt(0)
	v_mfma_f32_16x16x32_bf16 v[36:39], v[164:167], v[24:27], v[36:39]
	ds_read_b128 v[164:167], v170
	s_waitcnt lgkmcnt(0)
	v_mfma_f32_16x16x32_bf16 v[164:167], v[164:167], v[24:27], v[32:35]
	s_nop 2
	ds_read_b128 v[32:35], v171
	v_mfma_f32_16x16x32_bf16 v[238:241], v[238:241], v[24:27], v[242:245]
	s_waitcnt lgkmcnt(0)
	v_mfma_f32_16x16x32_bf16 v[168:171], v[32:35], v[24:27], v[28:31]
	ds_read_b128 v[24:27], v94 offset:128
	s_waitcnt vmcnt(5) lgkmcnt(0)
	v_mfma_f32_16x16x32_bf16 v[44:47], v[24:27], v[20:23], v[44:47]
	ds_read_b128 v[24:27], v94 offset:8576
	s_waitcnt lgkmcnt(0)
	v_mfma_f32_16x16x32_bf16 v[48:51], v[24:27], v[20:23], v[48:51]
	ds_read_b128 v[24:27], v94 offset:17024
	s_waitcnt lgkmcnt(0)
	v_mfma_f32_16x16x32_bf16 v[52:55], v[24:27], v[20:23], v[52:55]
	ds_read_b128 v[24:27], v94 offset:25472
	s_waitcnt lgkmcnt(0)
	v_mfma_f32_16x16x32_bf16 v[56:59], v[24:27], v[20:23], v[56:59]
	ds_read_b128 v[24:27], v94 offset:33920
	s_waitcnt lgkmcnt(0)
	v_mfma_f32_16x16x32_bf16 v[60:63], v[24:27], v[20:23], v[60:63]
	ds_read_b128 v[24:27], v94 offset:42368
	s_waitcnt lgkmcnt(0)
	v_mfma_f32_16x16x32_bf16 v[160:163], v[24:27], v[20:23], v[160:163]
	ds_read_b128 v[24:27], v94 offset:50816
	s_waitcnt lgkmcnt(0)
	v_mfma_f32_16x16x32_bf16 v[222:225], v[24:27], v[20:23], v[222:225]
	ds_read_b128 v[24:27], v94 offset:59264
	s_waitcnt lgkmcnt(0)
	v_mfma_f32_16x16x32_bf16 v[226:229], v[24:27], v[20:23], v[226:229]
	ds_read_b128 v[24:27], v172
	s_waitcnt lgkmcnt(0)
	v_mfma_f32_16x16x32_bf16 v[230:233], v[24:27], v[20:23], v[230:233]
	ds_read_b128 v[24:27], v173
	s_waitcnt lgkmcnt(0)
	v_mfma_f32_16x16x32_bf16 v[234:237], v[24:27], v[20:23], v[234:237]
	ds_read_b128 v[24:27], v174
	s_waitcnt lgkmcnt(0)
	v_mfma_f32_16x16x32_bf16 v[238:241], v[24:27], v[20:23], v[238:241]
	ds_read_b128 v[24:27], v175
	ds_read_b128 v[172:175], v182
	s_waitcnt lgkmcnt(1)
	v_mfma_f32_16x16x32_bf16 v[156:159], v[24:27], v[20:23], v[156:159]
	ds_read_b128 v[24:27], v176
	s_waitcnt lgkmcnt(0)
	v_mfma_f32_16x16x32_bf16 v[32:35], v[24:27], v[20:23], v[40:43]
	ds_read_b128 v[24:27], v177
	s_nop 1
	ds_read_b128 v[40:43], v94 offset:8640
	s_waitcnt lgkmcnt(1)
	v_mfma_f32_16x16x32_bf16 v[28:31], v[24:27], v[20:23], v[36:39]
	ds_read_b128 v[24:27], v178
	s_nop 1
	ds_read_b128 v[36:39], v179
	ds_read_b128 v[176:179], v183
	s_waitcnt lgkmcnt(2)
	v_mfma_f32_16x16x32_bf16 v[24:27], v[24:27], v[20:23], v[164:167]
	s_nop 2
	ds_read_b128 v[164:167], v180
	s_waitcnt lgkmcnt(2)
	v_mfma_f32_16x16x32_bf16 v[20:23], v[36:39], v[20:23], v[168:171]
	ds_read_b128 v[36:39], v94 offset:192
	s_waitcnt vmcnt(4) lgkmcnt(2)
	v_mfma_f32_16x16x32_bf16 v[156:159], v[176:179], v[16:19], v[156:159]
	ds_read_b128 v[176:179], v184
	ds_read_b128 v[168:171], v181
	s_waitcnt lgkmcnt(2)
	v_mfma_f32_16x16x32_bf16 v[36:39], v[36:39], v[16:19], v[44:47]
	s_nop 2
	ds_read_b128 v[44:47], v94 offset:17088
	v_mfma_f32_16x16x32_bf16 v[40:43], v[40:43], v[16:19], v[48:51]
	s_nop 2
	ds_read_b128 v[48:51], v94 offset:25536
	s_waitcnt lgkmcnt(3)
	v_mfma_f32_16x16x32_bf16 v[32:35], v[176:179], v[16:19], v[32:35]
	ds_read_b128 v[176:179], v185
	s_waitcnt lgkmcnt(2)
	v_mfma_f32_16x16x32_bf16 v[44:47], v[44:47], v[16:19], v[52:55]
	s_waitcnt lgkmcnt(1)
	v_mfma_f32_16x16x32_bf16 v[48:51], v[48:51], v[16:19], v[56:59]
	s_nop 0
	ds_read_b128 v[52:55], v94 offset:33984
	s_nop 0
	ds_read_b128 v[56:59], v94 offset:42432
	s_waitcnt lgkmcnt(2)
	v_mfma_f32_16x16x32_bf16 v[176:179], v[176:179], v[16:19], v[28:31]
	s_nop 2
	ds_read_b128 v[28:31], v186
	s_waitcnt lgkmcnt(2)
	v_mfma_f32_16x16x32_bf16 v[52:55], v[52:55], v[16:19], v[60:63]
	s_waitcnt lgkmcnt(1)
	v_mfma_f32_16x16x32_bf16 v[56:59], v[56:59], v[16:19], v[160:163]
	s_nop 0
	ds_read_b128 v[60:63], v94 offset:50880
	s_nop 0
	ds_read_b128 v[160:163], v94 offset:59328
	s_waitcnt lgkmcnt(2)
	v_mfma_f32_16x16x32_bf16 v[180:183], v[28:31], v[16:19], v[24:27]
	s_nop 2
	ds_read_b128 v[24:27], v187
	s_waitcnt lgkmcnt(2)
	v_mfma_f32_16x16x32_bf16 v[60:63], v[60:63], v[16:19], v[222:225]
	s_waitcnt lgkmcnt(1)
	v_mfma_f32_16x16x32_bf16 v[160:163], v[160:163], v[16:19], v[226:229]
	v_mfma_f32_16x16x32_bf16 v[164:167], v[164:167], v[16:19], v[230:233]
	v_mfma_f32_16x16x32_bf16 v[168:171], v[168:171], v[16:19], v[234:237]
	v_mfma_f32_16x16x32_bf16 v[172:175], v[172:175], v[16:19], v[238:241]
	s_waitcnt lgkmcnt(0)
	v_mfma_f32_16x16x32_bf16 v[184:187], v[24:27], v[16:19], v[20:23]
	ds_read_b128 v[16:19], v94 offset:256
	s_waitcnt vmcnt(3) lgkmcnt(0)
	v_mfma_f32_16x16x32_bf16 v[36:39], v[16:19], v[12:15], v[36:39]
	ds_read_b128 v[16:19], v94 offset:8704
	s_waitcnt lgkmcnt(0)
	v_mfma_f32_16x16x32_bf16 v[40:43], v[16:19], v[12:15], v[40:43]
	ds_read_b128 v[16:19], v94 offset:17152
	s_waitcnt lgkmcnt(0)
	v_mfma_f32_16x16x32_bf16 v[44:47], v[16:19], v[12:15], v[44:47]
	ds_read_b128 v[16:19], v94 offset:25600
	s_waitcnt lgkmcnt(0)
	v_mfma_f32_16x16x32_bf16 v[48:51], v[16:19], v[12:15], v[48:51]
	ds_read_b128 v[16:19], v94 offset:34048
	s_waitcnt lgkmcnt(0)
; #define LAS __attribute__((address_space(3)))
; #define MFMA16(a, b, c) __builtin_amdgcn_mfma_f32_16x16x32_bf16((a), (b), (c), 0, 0, 0)
; __device__ __forceinline__ void xattn_softmax(f32x4 (&s)[16], bf16x8 (&pf)[8], float& rinv) {
;     ...
;     for (int n = 0; n < 16; ++n) mx = fmaxf(mx, fmaxf(fmaxf(s[n][0], s[n][1]), fmaxf(s[n][2], s[n][3])));
; __device__ __forceinline__ void xattn_pair(LAS unsigned char* lds, int bh, size_t row_base, bf16* QO, const bf16* Kx, const bf16* VTx, int tid, const WsRef& wsr) {
;     ...
;         for (int kk = 0; kk < 8; ++kk)
; #pragma unroll
;             for (int n = 0; n < 16; ++n) { const bf16x8 kf = *(const LAS bf16x8*)(T + (n * 16 + fr) * LDX + kk * 32 + fq * 8); sx[n] = MFMA16(kf, qf[kk], sx[n]); }
	v_mfma_f32_16x16x32_bf16 v[52:55], v[16:19], v[12:15], v[52:55]
	ds_read_b128 v[16:19], v94 offset:42496
	s_waitcnt lgkmcnt(0)
	v_mfma_f32_16x16x32_bf16 v[56:59], v[16:19], v[12:15], v[56:59]
	ds_read_b128 v[16:19], v94 offset:50944
	s_waitcnt lgkmcnt(0)
	v_mfma_f32_16x16x32_bf16 v[60:63], v[16:19], v[12:15], v[60:63]
	ds_read_b128 v[16:19], v94 offset:59392
	s_waitcnt lgkmcnt(0)
	v_mfma_f32_16x16x32_bf16 v[160:163], v[16:19], v[12:15], v[160:163]
	ds_read_b128 v[16:19], v188
	s_waitcnt lgkmcnt(0)
	v_mfma_f32_16x16x32_bf16 v[164:167], v[16:19], v[12:15], v[164:167]
	ds_read_b128 v[16:19], v189
	s_waitcnt lgkmcnt(0)
	v_mfma_f32_16x16x32_bf16 v[168:171], v[16:19], v[12:15], v[168:171]
	ds_read_b128 v[16:19], v190
	s_waitcnt lgkmcnt(0)
	v_mfma_f32_16x16x32_bf16 v[172:175], v[16:19], v[12:15], v[172:175]
	ds_read_b128 v[16:19], v191
	s_waitcnt lgkmcnt(0)
	v_mfma_f32_16x16x32_bf16 v[28:31], v[16:19], v[12:15], v[156:159]
	ds_read_b128 v[16:19], v192
	s_nop 1
	ds_read_b128 v[156:159], v199
	s_waitcnt lgkmcnt(1)
	v_mfma_f32_16x16x32_bf16 v[24:27], v[16:19], v[12:15], v[32:35]
	ds_read_b128 v[16:19], v193
	s_nop 1
	ds_read_b128 v[32:35], v195
	s_waitcnt lgkmcnt(1)
	v_mfma_f32_16x16x32_bf16 v[20:23], v[16:19], v[12:15], v[176:179]
	ds_read_b128 v[16:19], v194
	s_waitcnt lgkmcnt(0)
	v_mfma_f32_16x16x32_bf16 v[16:19], v[16:19], v[12:15], v[180:183]
	v_mfma_f32_16x16x32_bf16 v[12:15], v[32:35], v[12:15], v[184:187]
	ds_read_b128 v[32:35], v94 offset:320
	s_waitcnt vmcnt(2) lgkmcnt(0)
	v_mfma_f32_16x16x32_bf16 v[32:35], v[32:35], v[8:11], v[36:39]
	s_nop 2
	ds_read_b128 v[36:39], v94 offset:8768
	s_waitcnt lgkmcnt(0)
	v_mfma_f32_16x16x32_bf16 v[36:39], v[36:39], v[8:11], v[40:43]
	s_nop 2
	ds_read_b128 v[40:43], v94 offset:17216
	s_waitcnt lgkmcnt(0)
	v_mfma_f32_16x16x32_bf16 v[40:43], v[40:43], v[8:11], v[44:47]
	s_nop 2
	ds_read_b128 v[44:47], v94 offset:25664
	s_waitcnt lgkmcnt(0)
	v_mfma_f32_16x16x32_bf16 v[44:47], v[44:47], v[8:11], v[48:51]
	s_nop 2
	ds_read_b128 v[48:51], v94 offset:34112
	v_mfma_f32_16x16x32_bf16 v[156:159], v[156:159], v[8:11], v[164:167]
	s_nop 2
	ds_read_b128 v[164:167], v197
	s_waitcnt lgkmcnt(1)
	v_mfma_f32_16x16x32_bf16 v[48:51], v[48:51], v[8:11], v[52:55]
	s_nop 2
	ds_read_b128 v[52:55], v94 offset:42560
	s_waitcnt lgkmcnt(0)
	v_mfma_f32_16x16x32_bf16 v[52:55], v[52:55], v[8:11], v[56:59]
	s_nop 2
	ds_read_b128 v[56:59], v94 offset:51008
	s_waitcnt lgkmcnt(0)
	v_mfma_f32_16x16x32_bf16 v[56:59], v[56:59], v[8:11], v[60:63]
	s_nop 2
	ds_read_b128 v[60:63], v94 offset:59456
	s_waitcnt lgkmcnt(0)
	v_mfma_f32_16x16x32_bf16 v[60:63], v[60:63], v[8:11], v[160:163]
	s_nop 2
	ds_read_b128 v[160:163], v196
	s_waitcnt lgkmcnt(0)
	v_mfma_f32_16x16x32_bf16 v[160:163], v[160:163], v[8:11], v[168:171]
	s_nop 2
	ds_read_b128 v[168:171], v198
	s_waitcnt lgkmcnt(0)
	v_mfma_f32_16x16x32_bf16 v[28:31], v[168:171], v[8:11], v[28:31]
	ds_read_b128 v[168:171], v200
	s_waitcnt lgkmcnt(0)
	v_mfma_f32_16x16x32_bf16 v[24:27], v[168:171], v[8:11], v[24:27]
	ds_read_b128 v[168:171], v201
	s_waitcnt lgkmcnt(0)
	v_mfma_f32_16x16x32_bf16 v[20:23], v[168:171], v[8:11], v[20:23]
	ds_read_b128 v[168:171], v202
	s_waitcnt lgkmcnt(0)
	v_mfma_f32_16x16x32_bf16 v[16:19], v[168:171], v[8:11], v[16:19]
	ds_read_b128 v[168:171], v203
	v_mfma_f32_16x16x32_bf16 v[164:167], v[164:167], v[8:11], v[172:175]
	s_waitcnt lgkmcnt(0)
	v_mfma_f32_16x16x32_bf16 v[8:11], v[168:171], v[8:11], v[12:15]
	s_nop 2
	ds_read_b128 v[12:15], v94 offset:384
	s_waitcnt vmcnt(1) lgkmcnt(0)
	v_mfma_f32_16x16x32_bf16 v[12:15], v[12:15], v[4:7], v[32:35]
	s_nop 2
	ds_read_b128 v[32:35], v94 offset:8832
	s_waitcnt lgkmcnt(0)
	v_mfma_f32_16x16x32_bf16 v[32:35], v[32:35], v[4:7], v[36:39]
	s_nop 2
	ds_read_b128 v[36:39], v94 offset:17280
	s_waitcnt lgkmcnt(0)
	v_mfma_f32_16x16x32_bf16 v[36:39], v[36:39], v[4:7], v[40:43]
	s_nop 2
	ds_read_b128 v[40:43], v94 offset:25728
	s_waitcnt lgkmcnt(0)
	v_mfma_f32_16x16x32_bf16 v[40:43], v[40:43], v[4:7], v[44:47]
	s_nop 2
	ds_read_b128 v[44:47], v94 offset:34176
	s_waitcnt lgkmcnt(0)
	v_mfma_f32_16x16x32_bf16 v[44:47], v[44:47], v[4:7], v[48:51]
	s_nop 2
	ds_read_b128 v[48:51], v94 offset:42624
	s_waitcnt lgkmcnt(0)
	v_mfma_f32_16x16x32_bf16 v[168:171], v[48:51], v[4:7], v[52:55]
	ds_read_b128 v[48:51], v94 offset:51072
	s_waitcnt lgkmcnt(0)
	v_mfma_f32_16x16x32_bf16 v[172:175], v[48:51], v[4:7], v[56:59]
	ds_read_b128 v[48:51], v94 offset:59520
	s_waitcnt lgkmcnt(0)
	v_mfma_f32_16x16x32_bf16 v[176:179], v[48:51], v[4:7], v[60:63]
	ds_read_b128 v[48:51], v209
	s_waitcnt lgkmcnt(0)
	v_mfma_f32_16x16x32_bf16 v[156:159], v[48:51], v[4:7], v[156:159]
	ds_read_b128 v[48:51], v211
	s_waitcnt lgkmcnt(0)
	v_mfma_f32_16x16x32_bf16 v[160:163], v[48:51], v[4:7], v[160:163]
	ds_read_b128 v[48:51], v215
	s_waitcnt lgkmcnt(0)
	v_mfma_f32_16x16x32_bf16 v[164:167], v[48:51], v[4:7], v[164:167]
	ds_read_b128 v[48:51], v216
	s_waitcnt lgkmcnt(0)
	v_mfma_f32_16x16x32_bf16 v[180:183], v[48:51], v[4:7], v[28:31]
	s_nop 2
	ds_read_b128 v[28:31], v217
	s_waitcnt lgkmcnt(0)
	v_mfma_f32_16x16x32_bf16 v[184:187], v[28:31], v[4:7], v[24:27]
	s_nop 2
	ds_read_b128 v[24:27], v218
	s_waitcnt lgkmcnt(0)
	v_mfma_f32_16x16x32_bf16 v[188:191], v[24:27], v[4:7], v[20:23]
	s_nop 2
	ds_read_b128 v[20:23], v219
	s_waitcnt lgkmcnt(0)
	v_mfma_f32_16x16x32_bf16 v[192:195], v[20:23], v[4:7], v[16:19]
	s_nop 2
	ds_read_b128 v[16:19], v220
	s_waitcnt lgkmcnt(0)
	v_mfma_f32_16x16x32_bf16 v[196:199], v[16:19], v[4:7], v[8:11]
	ds_read_b128 v[4:7], v94 offset:448
	s_waitcnt vmcnt(0) lgkmcnt(0)
	v_mfma_f32_16x16x32_bf16 v[60:63], v[4:7], v[0:3], v[12:15]
	ds_read_b128 v[4:7], v94 offset:8896
	s_nop 6
	v_max_f32_e32 v86, v63, v63
	s_waitcnt lgkmcnt(0)
; __device__ __forceinline__ float fexp2(float x) { return __builtin_amdgcn_exp2f(x); }
; __device__ __forceinline__ void xattn_softmax(f32x4 (&s)[16], bf16x8 (&pf)[8], float& rinv) {
;     ...
;     for (int n = 0; n < 16; ++n) mx = fmaxf(mx, fmaxf(fmaxf(s[n][0], s[n][1]), fmaxf(s[n][2], s[n][3])));
;     mx = fmaxf(mx, __shfl_xor(mx, 16)); mx = fmaxf(mx, __shfl_xor(mx, 32));
;     const float sc = 0.0625f * LOG2E; float sum = 0.f;
; #pragma unroll
;     for (int n = 0; n < 16; ++n)
; #pragma unroll
;         for (int r = 0; r < 4; ++r) { const float p = fexp2((s[n][r] - mx) * sc); s[n][r] = p; sum += p; }
	v_mfma_f32_16x16x32_bf16 v[56:59], v[4:7], v[0:3], v[32:35]
	ds_read_b128 v[4:7], v94 offset:17344
	v_max_f32_e32 v87, v62, v62
	v_max_f32_e32 v86, v87, v86
	s_waitcnt lgkmcnt(0)
	v_mfma_f32_16x16x32_bf16 v[52:55], v[4:7], v[0:3], v[36:39]
	ds_read_b128 v[4:7], v94 offset:25792
	s_nop 1
	v_max_f32_e32 v87, v59, v59
	v_max3_f32 v86, v60, v61, v86
	s_waitcnt lgkmcnt(0)
	v_mfma_f32_16x16x32_bf16 v[48:51], v[4:7], v[0:3], v[40:43]
	ds_read_b128 v[4:7], v94 offset:34240
	s_nop 6
	v_max_f32_e32 v99, v50, v50
	s_waitcnt lgkmcnt(0)
	v_mfma_f32_16x16x32_bf16 v[44:47], v[4:7], v[0:3], v[44:47]
	ds_read_b128 v[4:7], v94 offset:42688
	s_waitcnt lgkmcnt(0)
	v_mfma_f32_16x16x32_bf16 v[40:43], v[4:7], v[0:3], v[168:171]
	ds_read_b128 v[4:7], v94 offset:51136
	s_waitcnt lgkmcnt(0)
	v_mfma_f32_16x16x32_bf16 v[36:39], v[4:7], v[0:3], v[172:175]
	ds_read_b128 v[4:7], v94 offset:59584
	v_max_f32_e32 v94, v58, v58
	v_max_f32_e32 v87, v94, v87
	s_waitcnt lgkmcnt(0)
	v_mfma_f32_16x16x32_bf16 v[32:35], v[4:7], v[0:3], v[176:179]
	ds_read_b128 v[4:7], v205
	v_max3_f32 v87, v56, v57, v87
	v_max3_f32 v86, v86, s8, v87
	s_waitcnt lgkmcnt(0)
	v_mfma_f32_16x16x32_bf16 v[28:31], v[4:7], v[0:3], v[156:159]
	ds_read_b128 v[4:7], v206
	s_nop 1
	ds_read_b128 v[156:159], v214
	v_max_f32_e32 v87, v55, v55
	s_waitcnt lgkmcnt(1)
	v_mfma_f32_16x16x32_bf16 v[24:27], v[4:7], v[0:3], v[160:163]
	ds_read_b128 v[4:7], v207
	v_max_f32_e32 v94, v54, v54
	v_max_f32_e32 v87, v94, v87
	s_waitcnt lgkmcnt(0)
	v_mfma_f32_16x16x32_bf16 v[20:23], v[4:7], v[0:3], v[164:167]
	ds_read_b128 v[4:7], v208
	v_max_f32_e32 v94, v51, v51
	v_max_f32_e32 v94, v99, v94
	s_waitcnt lgkmcnt(0)
	v_mfma_f32_16x16x32_bf16 v[16:19], v[4:7], v[0:3], v[180:183]
	ds_read_b128 v[4:7], v210
	v_max3_f32 v87, v52, v53, v87
	v_max3_f32 v94, v48, v49, v94
	s_waitcnt lgkmcnt(0)
	v_mfma_f32_16x16x32_bf16 v[12:15], v[4:7], v[0:3], v[184:187]
	ds_read_b128 v[4:7], v212
	v_max3_f32 v86, v86, v87, v94
	v_max_f32_e32 v87, v47, v47
	v_max_f32_e32 v94, v46, v46
	v_max_f32_e32 v87, v94, v87
	v_max_f32_e32 v94, v43, v43
	v_max_f32_e32 v99, v42, v42
	v_max_f32_e32 v94, v99, v94
	v_max3_f32 v87, v44, v45, v87
	v_max3_f32 v94, v40, v41, v94
	v_max3_f32 v86, v86, v87, v94
	v_max_f32_e32 v87, v39, v39
	v_max_f32_e32 v94, v38, v38
	v_max_f32_e32 v87, v94, v87
	v_max_f32_e32 v94, v35, v35
	v_max_f32_e32 v99, v34, v34
	v_max_f32_e32 v94, v99, v94
	s_waitcnt lgkmcnt(0)
	v_mfma_f32_16x16x32_bf16 v[8:11], v[4:7], v[0:3], v[188:191]
	ds_read_b128 v[4:7], v213
	v_max3_f32 v87, v36, v37, v87
	v_max3_f32 v94, v32, v33, v94
	v_max3_f32 v86, v86, v87, v94
	v_max_f32_e32 v87, v31, v31
	v_max_f32_e32 v94, v30, v30
	v_max_f32_e32 v87, v94, v87
	v_max_f32_e32 v94, v27, v27
	v_max_f32_e32 v99, v26, v26
	v_max_f32_e32 v94, v99, v94
	v_max3_f32 v87, v28, v29, v87
	v_max3_f32 v94, v24, v25, v94
	v_max3_f32 v86, v86, v87, v94
	v_max_f32_e32 v87, v23, v23
	v_max_f32_e32 v94, v22, v22
	v_max_f32_e32 v87, v94, v87
	v_max_f32_e32 v94, v19, v19
	v_max_f32_e32 v99, v18, v18
	v_max_f32_e32 v94, v99, v94
	v_max3_f32 v87, v20, v21, v87
	v_max3_f32 v94, v16, v17, v94
	s_waitcnt lgkmcnt(0)
	v_mfma_f32_16x16x32_bf16 v[4:7], v[4:7], v[0:3], v[192:195]
	v_max3_f32 v86, v86, v87, v94
	v_max_f32_e32 v87, v15, v15
	v_max_f32_e32 v94, v14, v14
	v_mfma_f32_16x16x32_bf16 v[0:3], v[156:159], v[0:3], v[196:199]
	v_max_f32_e32 v87, v94, v87
	v_max_f32_e32 v94, v11, v11
	v_max_f32_e32 v99, v10, v10
	v_max_f32_e32 v94, v99, v94
	v_max3_f32 v87, v12, v13, v87
	v_max3_f32 v94, v8, v9, v94
	v_max3_f32 v86, v86, v87, v94
	v_max_f32_e32 v87, v7, v7
	v_max_f32_e32 v94, v6, v6
	v_max_f32_e32 v87, v94, v87
	v_max_f32_e32 v94, v3, v3
	v_max_f32_e32 v99, v2, v2
	v_max_f32_e32 v94, v99, v94
	v_max3_f32 v87, v4, v5, v87
	v_max3_f32 v94, v0, v1, v94
	v_max3_f32 v86, v86, v87, v94
	ds_bpermute_b32 v87, v155, v86
	s_waitcnt lgkmcnt(0)
	v_max_f32_e32 v87, v87, v87
	v_max_f32_e32 v86, v86, v87
	ds_bpermute_b32 v87, v64, v86
	s_waitcnt lgkmcnt(0)
	v_max_f32_e32 v87, v87, v87
	v_max_f32_e32 v99, v86, v87
	v_sub_f32_e32 v61, v61, v99
	v_sub_f32_e32 v60, v60, v99
	v_mul_f32_e32 v61, 0x3db8aa3b, v61
	v_mul_f32_e32 v60, 0x3db8aa3b, v60
	v_exp_f32_e32 v168, v61
	v_sub_f32_e32 v61, v62, v99
	v_exp_f32_e32 v165, v60
	v_mul_f32_e32 v61, 0x3db8aa3b, v61
	v_exp_f32_e32 v167, v61
	v_sub_f32_e32 v61, v63, v99
	v_sub_f32_e32 v57, v57, v99
	v_mul_f32_e32 v61, 0x3db8aa3b, v61
	v_sub_f32_e32 v56, v56, v99
	v_mul_f32_e32 v57, 0x3db8aa3b, v57
	v_exp_f32_e32 v170, v61
	v_mul_f32_e32 v56, 0x3db8aa3b, v56
	v_exp_f32_e32 v174, v57
	v_sub_f32_e32 v57, v58, v99
	v_add_f32_e32 v60, 0, v165
	v_exp_f32_e32 v173, v56
	v_mul_f32_e32 v57, 0x3db8aa3b, v57
	v_add_f32_e32 v60, v168, v60
	v_exp_f32_e32 v175, v57
	v_sub_f32_e32 v57, v59, v99
	v_sub_f32_e32 v53, v53, v99
	v_add_f32_e32 v60, v167, v60
	v_mul_f32_e32 v57, 0x3db8aa3b, v57
	v_sub_f32_e32 v52, v52, v99
	v_mul_f32_e32 v53, 0x3db8aa3b, v53
	v_add_f32_e32 v60, v170, v60
	v_exp_f32_e32 v176, v57
	v_mul_f32_e32 v52, 0x3db8aa3b, v52
	v_exp_f32_e32 v160, v53
	v_sub_f32_e32 v53, v54, v99
	v_add_f32_e32 v56, v173, v60
	v_exp_f32_e32 v62, v52
	v_mul_f32_e32 v53, 0x3db8aa3b, v53
	v_add_f32_e32 v56, v174, v56
	v_exp_f32_e32 v54, v53
	v_sub_f32_e32 v53, v55, v99
	v_sub_f32_e32 v49, v49, v99
	v_add_f32_e32 v56, v175, v56
	v_mul_f32_e32 v53, 0x3db8aa3b, v53
	v_sub_f32_e32 v48, v48, v99
	v_mul_f32_e32 v49, 0x3db8aa3b, v49
	v_add_f32_e32 v56, v176, v56
	v_exp_f32_e32 v161, v53
	v_mul_f32_e32 v48, 0x3db8aa3b, v48
	v_exp_f32_e32 v169, v49
	v_sub_f32_e32 v49, v50, v99
	v_add_f32_e32 v52, v62, v56
	v_exp_f32_e32 v166, v48
	v_mul_f32_e32 v49, 0x3db8aa3b, v49
	v_add_f32_e32 v52, v160, v52
; #define LAS __attribute__((address_space(3)))
; __device__ __forceinline__ float fexp2(float x) { return __builtin_amdgcn_exp2f(x); }
; __device__ __forceinline__ void xattn_softmax(f32x4 (&s)[16], bf16x8 (&pf)[8], float& rinv) {
;     ...
;         for (int r = 0; r < 4; ++r) { const float p = fexp2((s[n][r] - mx) * sc); s[n][r] = p; sum += p; }
;     sum += __shfl_xor(sum, 16); sum += __shfl_xor(sum, 32);
; __device__ __forceinline__ void xattn_pair(LAS unsigned char* lds, int bh, size_t row_base, bf16* QO, const bf16* Kx, const bf16* VTx, int tid, const WsRef& wsr) {
;     ...
;     __syncthreads();
;     const u32x4* vg = (const u32x4*)(VTx + (size_t)bh * 65536);
; #pragma unroll 4
;     for (int i = 0; i < 16; ++i) { const int id = tid + 512 * i, r = id >> 5, ch = id & 31; *(LAS u32x4*)(T + r * LDX + ch * 8) = vg[id]; }
	v_exp_f32_e32 v171, v49
	v_sub_f32_e32 v49, v51, v99
	v_add_f32_e32 v52, v54, v52
	v_mul_f32_e32 v49, 0x3db8aa3b, v49
	v_sub_f32_e32 v44, v44, v99
	v_add_f32_e32 v52, v161, v52
	v_exp_f32_e32 v172, v49
	v_mul_f32_e32 v44, 0x3db8aa3b, v44
	v_sub_f32_e32 v45, v45, v99
	v_add_f32_e32 v48, v166, v52
	v_exp_f32_e32 v44, v44
	v_mul_f32_e32 v45, 0x3db8aa3b, v45
	v_sub_f32_e32 v46, v46, v99
	v_add_f32_e32 v48, v169, v48
	v_exp_f32_e32 v45, v45
	v_mul_f32_e32 v46, 0x3db8aa3b, v46
	v_sub_f32_e32 v47, v47, v99
	v_sub_f32_e32 v41, v41, v99
	v_add_f32_e32 v48, v171, v48
	v_exp_f32_e32 v52, v46
	v_mul_f32_e32 v47, 0x3db8aa3b, v47
	v_sub_f32_e32 v40, v40, v99
	v_mul_f32_e32 v41, 0x3db8aa3b, v41
	v_add_f32_e32 v48, v172, v48
	v_exp_f32_e32 v53, v47
	v_mul_f32_e32 v40, 0x3db8aa3b, v40
	v_exp_f32_e32 v163, v41
	v_sub_f32_e32 v41, v42, v99
	v_add_f32_e32 v48, v44, v48
	v_exp_f32_e32 v55, v40
	v_mul_f32_e32 v41, 0x3db8aa3b, v41
	v_add_f32_e32 v48, v45, v48
	v_exp_f32_e32 v164, v41
	v_sub_f32_e32 v41, v43, v99
	v_sub_f32_e32 v37, v37, v99
	v_add_f32_e32 v46, v52, v48
	v_mul_f32_e32 v41, 0x3db8aa3b, v41
	v_sub_f32_e32 v36, v36, v99
	v_mul_f32_e32 v37, 0x3db8aa3b, v37
	v_add_f32_e32 v46, v53, v46
	v_exp_f32_e32 v43, v41
	v_mul_f32_e32 v36, 0x3db8aa3b, v36
	v_exp_f32_e32 v50, v37
	v_sub_f32_e32 v37, v38, v99
	v_add_f32_e32 v40, v55, v46
	v_exp_f32_e32 v48, v36
	v_mul_f32_e32 v37, 0x3db8aa3b, v37
	v_add_f32_e32 v40, v163, v40
	v_exp_f32_e32 v49, v37
	v_sub_f32_e32 v37, v39, v99
	v_sub_f32_e32 v33, v33, v99
	v_add_f32_e32 v40, v164, v40
	v_mul_f32_e32 v37, 0x3db8aa3b, v37
	v_sub_f32_e32 v32, v32, v99
	v_mul_f32_e32 v33, 0x3db8aa3b, v33
	v_add_f32_e32 v40, v43, v40
	v_exp_f32_e32 v51, v37
	v_mul_f32_e32 v32, 0x3db8aa3b, v32
	v_exp_f32_e32 v61, v33
	v_sub_f32_e32 v33, v34, v99
	v_add_f32_e32 v36, v48, v40
	v_exp_f32_e32 v60, v32
	v_mul_f32_e32 v33, 0x3db8aa3b, v33
	v_add_f32_e32 v36, v50, v36
	v_exp_f32_e32 v63, v33
	v_sub_f32_e32 v33, v35, v99
	v_sub_f32_e32 v29, v29, v99
	v_add_f32_e32 v36, v49, v36
	v_mul_f32_e32 v33, 0x3db8aa3b, v33
	v_sub_f32_e32 v28, v28, v99
	v_mul_f32_e32 v29, 0x3db8aa3b, v29
	v_add_f32_e32 v36, v51, v36
	v_exp_f32_e32 v162, v33
	v_mul_f32_e32 v28, 0x3db8aa3b, v28
	v_exp_f32_e32 v58, v29
	v_sub_f32_e32 v29, v30, v99
	v_add_f32_e32 v32, v60, v36
	v_exp_f32_e32 v56, v28
	v_mul_f32_e32 v29, 0x3db8aa3b, v29
	v_add_f32_e32 v32, v61, v32
	v_exp_f32_e32 v57, v29
	v_sub_f32_e32 v29, v31, v99
	v_sub_f32_e32 v25, v25, v99
	v_add_f32_e32 v32, v63, v32
	v_mul_f32_e32 v29, 0x3db8aa3b, v29
	v_sub_f32_e32 v24, v24, v99
	v_mul_f32_e32 v25, 0x3db8aa3b, v25
	v_add_f32_e32 v32, v162, v32
	v_exp_f32_e32 v59, v29
	v_mul_f32_e32 v24, 0x3db8aa3b, v24
	v_exp_f32_e32 v157, v25
	v_sub_f32_e32 v25, v26, v99
	v_add_f32_e32 v28, v56, v32
	v_exp_f32_e32 v156, v24
	v_mul_f32_e32 v25, 0x3db8aa3b, v25
	v_add_f32_e32 v28, v58, v28
	v_exp_f32_e32 v158, v25
	v_sub_f32_e32 v25, v27, v99
	v_sub_f32_e32 v21, v21, v99
	v_add_f32_e32 v28, v57, v28
	v_mul_f32_e32 v25, 0x3db8aa3b, v25
	v_sub_f32_e32 v20, v20, v99
	v_mul_f32_e32 v21, 0x3db8aa3b, v21
	v_add_f32_e32 v28, v59, v28
	v_exp_f32_e32 v159, v25
	v_mul_f32_e32 v20, 0x3db8aa3b, v20
	v_exp_f32_e32 v38, v21
	v_sub_f32_e32 v21, v22, v99
	v_add_f32_e32 v24, v156, v28
	v_exp_f32_e32 v36, v20
	v_mul_f32_e32 v21, 0x3db8aa3b, v21
	v_add_f32_e32 v24, v157, v24
	v_exp_f32_e32 v37, v21
	v_sub_f32_e32 v21, v23, v99
	v_sub_f32_e32 v17, v17, v99
	v_add_f32_e32 v24, v158, v24
	v_mul_f32_e32 v21, 0x3db8aa3b, v21
	v_sub_f32_e32 v16, v16, v99
	v_mul_f32_e32 v17, 0x3db8aa3b, v17
	v_add_f32_e32 v24, v159, v24
	v_exp_f32_e32 v39, v21
	v_mul_f32_e32 v16, 0x3db8aa3b, v16
	v_exp_f32_e32 v87, v17
	v_sub_f32_e32 v17, v18, v99
	v_add_f32_e32 v20, v36, v24
	v_exp_f32_e32 v86, v16
	v_mul_f32_e32 v17, 0x3db8aa3b, v17
	v_add_f32_e32 v20, v38, v20
	v_exp_f32_e32 v94, v17
	v_sub_f32_e32 v17, v19, v99
	v_add_f32_e32 v20, v37, v20
	v_mul_f32_e32 v17, 0x3db8aa3b, v17
	v_sub_f32_e32 v12, v12, v99
	v_add_f32_e32 v20, v39, v20
	v_exp_f32_e32 v19, v17
	v_mul_f32_e32 v12, 0x3db8aa3b, v12
	v_sub_f32_e32 v13, v13, v99
	v_add_f32_e32 v16, v86, v20
	v_exp_f32_e32 v12, v12
	v_mul_f32_e32 v13, 0x3db8aa3b, v13
	v_sub_f32_e32 v14, v14, v99
	v_add_f32_e32 v16, v87, v16
	v_exp_f32_e32 v13, v13
	v_mul_f32_e32 v14, 0x3db8aa3b, v14
	v_sub_f32_e32 v15, v15, v99
	v_add_f32_e32 v16, v94, v16
	v_exp_f32_e32 v14, v14
	v_mul_f32_e32 v15, 0x3db8aa3b, v15
	v_add_f32_e32 v16, v19, v16
	v_exp_f32_e32 v15, v15
	v_add_f32_e32 v16, v12, v16
	v_add_f32_e32 v16, v13, v16
	v_sub_f32_e32 v8, v8, v99
	v_add_f32_e32 v16, v14, v16
	v_mul_f32_e32 v8, 0x3db8aa3b, v8
	v_add_f32_e32 v17, v15, v16
	v_exp_f32_e32 v16, v8
	v_sub_f32_e32 v9, v9, v99
	v_mul_f32_e32 v9, 0x3db8aa3b, v9
	v_sub_f32_e32 v4, v4, v99
	v_add_f32_e32 v8, v16, v17
	v_exp_f32_e32 v17, v9
	v_mul_f32_e32 v4, 0x3db8aa3b, v4
	v_sub_f32_e32 v5, v5, v99
	v_exp_f32_e32 v4, v4
	v_add_f32_e32 v9, v17, v8
	v_sub_f32_e32 v8, v10, v99
	v_mul_f32_e32 v8, 0x3db8aa3b, v8
	v_exp_f32_e32 v8, v8
	v_mul_f32_e32 v5, 0x3db8aa3b, v5
	v_sub_f32_e32 v6, v6, v99
	v_exp_f32_e32 v5, v5
	v_add_f32_e32 v10, v8, v9
	v_sub_f32_e32 v9, v11, v99
	v_mul_f32_e32 v9, 0x3db8aa3b, v9
	v_exp_f32_e32 v9, v9
	v_mul_f32_e32 v6, 0x3db8aa3b, v6
	v_sub_f32_e32 v7, v7, v99
	v_exp_f32_e32 v6, v6
	v_mul_f32_e32 v7, 0x3db8aa3b, v7
	v_add_f32_e32 v10, v9, v10
	v_exp_f32_e32 v7, v7
	v_add_f32_e32 v10, v4, v10
	v_add_f32_e32 v10, v5, v10
	v_sub_f32_e32 v0, v0, v99
	v_add_f32_e32 v10, v6, v10
	v_mul_f32_e32 v0, 0x3db8aa3b, v0
	v_add_f32_e32 v11, v7, v10
	v_exp_f32_e32 v10, v0
	v_sub_f32_e32 v1, v1, v99
	v_mul_f32_e32 v1, 0x3db8aa3b, v1
	v_exp_f32_e32 v18, v1
	v_sub_f32_e32 v1, v2, v99
	v_mul_f32_e32 v1, 0x3db8aa3b, v1
	v_add_f32_e32 v0, v10, v11
	v_exp_f32_e32 v11, v1
	v_sub_f32_e32 v1, v3, v99
	v_mul_f32_e32 v1, 0x3db8aa3b, v1
	v_exp_f32_e32 v3, v1
	v_add_f32_e32 v0, v18, v0
	v_add_f32_e32 v0, v11, v0
	v_add_f32_e32 v0, v3, v0
	ds_bpermute_b32 v1, v155, v0
	v_lshrrev_b32_e32 v2, 5, v93
	v_mul_u32_u24_e32 v2, 0x210, v2
	v_add3_u32 v2, v2, v92, 0
	s_mov_b64 s[8:9], 0
	s_waitcnt lgkmcnt(0)
	s_barrier
